# dilated attention softmax: tile-uniform bounds test + 5-VALU per-score bias/mask (was 7 VALU + 1 SALU)
# speedup vs baseline: 1.0028x; 1.0028x over previous
.LBB0_553:
	v_lshlrev_b32_e32 v8, 5, v195
	v_and_b32_e32 v5, 24, v5
	s_movk_i32 s19, 0xe0
	v_and_or_b32 v5, v8, s19, v5
	v_add_u32_e32 v8, 32, v195
	v_lshrrev_b32_e32 v6, 5, v4
	v_lshrrev_b32_e32 v7, 5, v2
	s_mov_b32 s22, 0x7ffffc
	v_lshrrev_b32_e32 v9, 1, v8
	v_and_or_b32 v6, v6, s22, v7
	v_lshlrev_b32_e32 v5, 1, v5
	v_and_or_b32 v7, v9, s22, v7
	v_lshl_or_b32 v6, v6, 9, v5
	v_lshl_or_b32 v5, v7, 9, v5
	v_add_u32_e32 v196, 0, v6
	v_add_u32_e32 v197, 0, v5
	v_lshlrev_b32_e32 v5, 1, v2
	v_lshlrev_b32_e32 v6, 8, v195
	v_and_b32_e32 v7, 0x70, v4
	v_bitop3_b32 v6, v5, v6, v7 bitop3:0xde
	v_add_u32_e32 v198, 0, v6
	v_lshlrev_b32_e32 v6, 8, v8
	v_bitop3_b32 v5, v5, v6, v7 bitop3:0xde
	v_add_u32_e32 v199, 0, v5
	v_add_u32_e32 v5, 0x80, v209
	s_movk_i32 s19, 0xff7f
	v_add_u32_e32 v8, 0xa0, v209
	v_min_i32_e32 v5, s3, v5
	v_cmp_lt_i32_e32 vcc, s19, v209
	s_movk_i32 s19, 0xff5f
	s_waitcnt vmcnt(7)
	ds_write_b128 v196, v[162:165]
	v_cndmask_b32_e32 v6, 0, v5, vcc
	v_min_i32_e32 v5, s3, v8
	v_cmp_lt_i32_e32 vcc, s19, v209
	v_ashrrev_i32_e32 v7, 31, v6
	v_lshlrev_b64 v[6:7], s18, v[6:7]
	v_cndmask_b32_e32 v8, 0, v5, vcc
	v_ashrrev_i32_e32 v9, 31, v8
	v_lshlrev_b64 v[8:9], s18, v[8:9]
	v_lshl_add_u64 v[6:7], v[6:7], 0, v[2:3]
	v_lshl_add_u64 v[8:9], v[8:9], 0, v[2:3]
	v_lshlrev_b64 v[6:7], 1, v[6:7]
	v_lshlrev_b64 v[8:9], 1, v[8:9]
	v_lshl_add_u64 v[10:11], s[12:13], 0, v[6:7]
	v_lshl_add_u64 v[12:13], s[12:13], 0, v[8:9]
	v_lshl_add_u64 v[8:9], s[10:11], 0, v[8:9]
	s_waitcnt vmcnt(6)
	ds_write_b128 v197, v[158:161]
	s_waitcnt vmcnt(5)
	ds_write_b128 v198, v[154:157] offset:32768
	s_waitcnt vmcnt(4)
	ds_write_b128 v199, v[150:153] offset:32768
	s_waitcnt lgkmcnt(0)
	s_barrier
	s_waitcnt vmcnt(0)
	global_load_dwordx4 v[150:153], v[10:11], off
	global_load_dwordx4 v[154:157], v[12:13], off
	v_lshl_add_u64 v[6:7], s[10:11], 0, v[6:7]
	global_load_dwordx4 v[166:169], v[8:9], off
	global_load_dwordx4 v[170:173], v[6:7], off
	s_cmp_lg_u32 0, -1
	s_cselect_b32 s19, 0, 0
	v_cvt_f32_u32_e32 v7, s16
	s_lshl_b32 s16, s31, 1
	s_or_b32 s16, s16, 1
	v_cvt_f32_ubyte0_e32 v8, s16
	v_and_b32_e32 v189, 63, v4
	v_mul_f32_e32 v8, -0.5, v8
	v_lshlrev_b32_e32 v5, 4, v189
	v_exp_f32_e32 v8, v8
	v_lshlrev_b32_e32 v4, 3, v189
	v_and_b32_e32 v5, 0xc0, v5
	v_lshlrev_b32_e32 v6, 1, v189
	v_and_or_b32 v5, v4, 24, v5
	v_and_b32_e32 v6, 32, v6
	v_and_b32_e32 v4, 0x100, v4
	s_and_b32 s16, s17, 0x3fffffc0
	v_or3_b32 v87, v5, v6, v4
	v_mul_f32_e32 v4, 0xbfb8aa3b, v7
	s_lshl_b32 s16, s16, 2
	v_lshlrev_b32_e32 v190, 4, v188
	v_lshlrev_b32_e32 v5, 4, v187
	v_mul_f32_e32 v193, v8, v4
	s_add_i32 s44, s16, 0
	s_ashr_i32 s46, s17, 7
	v_and_b32_e32 v5, 0x70, v5
	v_or_b32_e32 v7, 32, v190
	v_or_b32_e32 v8, 64, v190
	v_or_b32_e32 v9, 0x60, v190
	v_or_b32_e32 v10, 0x80, v190
	v_or_b32_e32 v11, 0xa0, v190
	v_or_b32_e32 v12, 0xc0, v190
	v_or_b32_e32 v13, 0xe0, v190
	v_add_u32_e32 v208, s19, v87
	s_add_i32 s44, s44, 0x10000
	v_lshlrev_b32_e32 v4, 8, v187
	v_xad_u32 v6, v190, v5, 0
	v_xad_u32 v7, v7, v5, 0
	v_xad_u32 v8, v8, v5, 0
	v_xad_u32 v9, v9, v5, 0
	v_xad_u32 v10, v10, v5, 0
	v_xad_u32 v11, v11, v5, 0
	v_xad_u32 v12, v12, v5, 0
	v_xad_u32 v5, v13, v5, 0
	v_lshlrev_b32_e32 v185, 2, v188
	s_add_i32 s19, s46, -1
	v_add_u32_e32 v194, s27, v185
	v_cmp_gt_u32_e64 s[38:39], 32, v189
	v_lshl_add_u32 v191, v187, 2, s44
	s_cmp_lt_u32 s19, -3
	v_add_u32_e32 v207, v6, v4
	v_add_u32_e32 v206, v7, v4
	v_add_u32_e32 v205, v8, v4
	v_add_u32_e32 v204, v9, v4
	v_add_u32_e32 v203, v10, v4
	v_add_u32_e32 v202, v11, v4
	v_add_u32_e32 v201, v12, v4
	v_add_u32_e32 v200, v5, v4
	s_cbranch_scc1 .LBB0_558
	ds_read_b128 v[4:7], v207 offset:32768
	ds_read_b128 v[8:11], v207 offset:40960
	ds_read_b128 v[36:39], v206 offset:32768
	ds_read_b128 v[40:43], v206 offset:40960
	s_waitcnt lgkmcnt(3)
	v_mfma_f32_32x32x16_bf16 v[20:35], v[4:7], v[110:113], 0
	s_waitcnt lgkmcnt(2)
	v_mfma_f32_32x32x16_bf16 v[4:19], v[8:11], v[110:113], 0
	ds_read_b128 v[44:47], v205 offset:32768
	ds_read_b128 v[48:51], v205 offset:40960
	s_waitcnt lgkmcnt(3)
	v_mfma_f32_32x32x16_bf16 v[20:35], v[36:39], v[130:133], v[20:35]
	s_waitcnt lgkmcnt(2)
	v_mfma_f32_32x32x16_bf16 v[4:19], v[40:43], v[130:133], v[4:19]
	ds_read_b128 v[36:39], v204 offset:32768
	ds_read_b128 v[40:43], v204 offset:40960
	s_waitcnt lgkmcnt(3)
	v_mfma_f32_32x32x16_bf16 v[20:35], v[44:47], v[126:129], v[20:35]
	s_waitcnt lgkmcnt(2)
	v_mfma_f32_32x32x16_bf16 v[4:19], v[48:51], v[126:129], v[4:19]
	ds_read_b128 v[44:47], v203 offset:32768
	ds_read_b128 v[48:51], v203 offset:40960
	s_waitcnt lgkmcnt(3)
	v_mfma_f32_32x32x16_bf16 v[20:35], v[36:39], v[122:125], v[20:35]
	s_waitcnt lgkmcnt(2)
	v_mfma_f32_32x32x16_bf16 v[4:19], v[40:43], v[122:125], v[4:19]
	ds_read_b128 v[36:39], v202 offset:32768
	ds_read_b128 v[40:43], v202 offset:40960
	s_waitcnt lgkmcnt(3)
	v_mfma_f32_32x32x16_bf16 v[20:35], v[44:47], v[118:121], v[20:35]
	s_waitcnt lgkmcnt(2)
	v_mfma_f32_32x32x16_bf16 v[4:19], v[48:51], v[118:121], v[4:19]
	ds_read_b128 v[44:47], v201 offset:32768
	ds_read_b128 v[48:51], v201 offset:40960
	s_waitcnt lgkmcnt(3)
	v_mfma_f32_32x32x16_bf16 v[20:35], v[36:39], v[114:117], v[20:35]
	s_waitcnt lgkmcnt(2)
	v_mfma_f32_32x32x16_bf16 v[4:19], v[40:43], v[114:117], v[4:19]
	ds_read_b128 v[36:39], v200 offset:32768
	ds_read_b128 v[40:43], v200 offset:40960
	s_waitcnt lgkmcnt(3)
	v_mfma_f32_32x32x16_bf16 v[20:35], v[44:47], v[106:109], v[20:35]
	s_waitcnt lgkmcnt(2)
	v_mfma_f32_32x32x16_bf16 v[4:19], v[48:51], v[106:109], v[4:19]
	s_waitcnt lgkmcnt(1)
	v_mfma_f32_32x32x16_bf16 v[20:35], v[36:39], v[102:105], v[20:35]
	s_waitcnt lgkmcnt(0)
	v_mfma_f32_32x32x16_bf16 v[4:19], v[40:43], v[102:105], v[4:19]
	v_sub_u32_e32 v36, v192, v194
	v_cvt_f32_i32_e32 v36, v36
	v_readfirstlane_b32 s40, v194
	s_add_i32 s41, s40, 64
	s_cmp_lt_i32 s40, 0
	s_cbranch_scc1 .Lam_out_0
	s_cmp_gt_i32 s41, s45
	s_cbranch_scc1 .Lam_out_0
	v_add_f32_e32 v37, 0xc2000000, v36
	v_mov_b32_e32 v38, v36
	v_cmp_le_f32_e64 vcc, |v37|, s76
	v_cmp_le_f32_e64 s[16:17], |v38|, s76
	v_mul_f32_e64 v37, v193, |v37|
	v_mul_f32_e64 v38, v193, |v38|
	v_fmac_f32_e32 v37, 0x3e0293ee, v4
	v_fmac_f32_e32 v38, 0x3e0293ee, v20
	v_cndmask_b32_e32 v4, v234, v37, vcc
	v_cndmask_b32_e64 v20, v234, v38, s[16:17]
	v_add_f32_e32 v37, -1.0, v36
	v_add_f32_e32 v38, 0xc2040000, v36
	v_cmp_le_f32_e64 vcc, |v37|, s76
	v_cmp_le_f32_e64 s[16:17], |v38|, s76
	v_mul_f32_e64 v37, v193, |v37|
	v_mul_f32_e64 v38, v193, |v38|
	v_fmac_f32_e32 v37, 0x3e0293ee, v21
	v_fmac_f32_e32 v38, 0x3e0293ee, v5
	v_cndmask_b32_e32 v21, v234, v37, vcc
	v_cndmask_b32_e64 v5, v234, v38, s[16:17]
	v_add_f32_e32 v37, -2.0, v36
	v_add_f32_e32 v38, 0xc2080000, v36
	v_cmp_le_f32_e64 vcc, |v37|, s76
	v_cmp_le_f32_e64 s[16:17], |v38|, s76
	v_mul_f32_e64 v37, v193, |v37|
	v_mul_f32_e64 v38, v193, |v38|
	v_fmac_f32_e32 v37, 0x3e0293ee, v22
	v_fmac_f32_e32 v38, 0x3e0293ee, v6
	v_cndmask_b32_e32 v22, v234, v37, vcc
	v_cndmask_b32_e64 v6, v234, v38, s[16:17]
	v_add_f32_e32 v37, 0xc0400000, v36
	v_add_f32_e32 v38, 0xc20c0000, v36
	v_cmp_le_f32_e64 vcc, |v37|, s76
	v_cmp_le_f32_e64 s[16:17], |v38|, s76
	v_mul_f32_e64 v37, v193, |v37|
	v_mul_f32_e64 v38, v193, |v38|
	v_fmac_f32_e32 v37, 0x3e0293ee, v23
	v_fmac_f32_e32 v38, 0x3e0293ee, v7
	v_cndmask_b32_e32 v23, v234, v37, vcc
	v_cndmask_b32_e64 v7, v234, v38, s[16:17]
	v_add_f32_e32 v37, 0xc1000000, v36
	v_add_f32_e32 v38, 0xc2200000, v36
	v_cmp_le_f32_e64 vcc, |v37|, s76
	v_cmp_le_f32_e64 s[16:17], |v38|, s76
	v_mul_f32_e64 v37, v193, |v37|
	v_mul_f32_e64 v38, v193, |v38|
	v_fmac_f32_e32 v37, 0x3e0293ee, v24
	v_fmac_f32_e32 v38, 0x3e0293ee, v8
	v_cndmask_b32_e32 v24, v234, v37, vcc
	v_cndmask_b32_e64 v8, v234, v38, s[16:17]
	v_add_f32_e32 v37, 0xc1100000, v36
	v_add_f32_e32 v38, 0xc2240000, v36
	v_cmp_le_f32_e64 vcc, |v37|, s76
	v_cmp_le_f32_e64 s[16:17], |v38|, s76
	v_mul_f32_e64 v37, v193, |v37|
	v_mul_f32_e64 v38, v193, |v38|
	v_fmac_f32_e32 v37, 0x3e0293ee, v25
	v_fmac_f32_e32 v38, 0x3e0293ee, v9
	v_cndmask_b32_e32 v25, v234, v37, vcc
	v_cndmask_b32_e64 v9, v234, v38, s[16:17]
	v_add_f32_e32 v37, 0xc1200000, v36
	v_add_f32_e32 v38, 0xc2280000, v36
	v_cmp_le_f32_e64 vcc, |v37|, s76
	v_cmp_le_f32_e64 s[16:17], |v38|, s76
	v_mul_f32_e64 v37, v193, |v37|
	v_mul_f32_e64 v38, v193, |v38|
	v_fmac_f32_e32 v37, 0x3e0293ee, v26
	v_fmac_f32_e32 v38, 0x3e0293ee, v10
	v_cndmask_b32_e32 v26, v234, v37, vcc
	v_cndmask_b32_e64 v10, v234, v38, s[16:17]
	v_add_f32_e32 v37, 0xc1300000, v36
	v_add_f32_e32 v38, 0xc22c0000, v36
	v_cmp_le_f32_e64 vcc, |v37|, s76
	v_cmp_le_f32_e64 s[16:17], |v38|, s76
	v_mul_f32_e64 v37, v193, |v37|
	v_mul_f32_e64 v38, v193, |v38|
	v_fmac_f32_e32 v37, 0x3e0293ee, v27
	v_fmac_f32_e32 v38, 0x3e0293ee, v11
	v_cndmask_b32_e32 v27, v234, v37, vcc
	v_cndmask_b32_e64 v11, v234, v38, s[16:17]
	v_add_f32_e32 v37, 0xc1800000, v36
	v_add_f32_e32 v38, 0xc2400000, v36
	v_cmp_le_f32_e64 vcc, |v37|, s76
	v_cmp_le_f32_e64 s[16:17], |v38|, s76
	v_mul_f32_e64 v37, v193, |v37|
	v_mul_f32_e64 v38, v193, |v38|
	v_fmac_f32_e32 v37, 0x3e0293ee, v28
	v_fmac_f32_e32 v38, 0x3e0293ee, v12
	v_cndmask_b32_e32 v28, v234, v37, vcc
	v_cndmask_b32_e64 v12, v234, v38, s[16:17]
	v_add_f32_e32 v37, 0xc1880000, v36
	v_add_f32_e32 v38, 0xc2440000, v36
	v_cmp_le_f32_e64 vcc, |v37|, s76
	v_cmp_le_f32_e64 s[16:17], |v38|, s76
	v_mul_f32_e64 v37, v193, |v37|
	v_mul_f32_e64 v38, v193, |v38|
	v_fmac_f32_e32 v37, 0x3e0293ee, v29
	v_fmac_f32_e32 v38, 0x3e0293ee, v13
	v_cndmask_b32_e32 v29, v234, v37, vcc
	v_cndmask_b32_e64 v13, v234, v38, s[16:17]
	v_add_f32_e32 v37, 0xc1900000, v36
	v_add_f32_e32 v38, 0xc2480000, v36
	v_cmp_le_f32_e64 vcc, |v37|, s76
	v_cmp_le_f32_e64 s[16:17], |v38|, s76
	v_mul_f32_e64 v37, v193, |v37|
	v_mul_f32_e64 v38, v193, |v38|
	v_fmac_f32_e32 v37, 0x3e0293ee, v30
	v_fmac_f32_e32 v38, 0x3e0293ee, v14
	v_cndmask_b32_e32 v30, v234, v37, vcc
	v_cndmask_b32_e64 v14, v234, v38, s[16:17]
	v_add_f32_e32 v37, 0xc1980000, v36
	v_add_f32_e32 v38, 0xc24c0000, v36
	v_cmp_le_f32_e64 vcc, |v37|, s76
	v_cmp_le_f32_e64 s[16:17], |v38|, s76
	v_mul_f32_e64 v37, v193, |v37|
	v_mul_f32_e64 v38, v193, |v38|
	v_fmac_f32_e32 v37, 0x3e0293ee, v31
	v_fmac_f32_e32 v38, 0x3e0293ee, v15
	v_cndmask_b32_e32 v31, v234, v37, vcc
	v_cndmask_b32_e64 v15, v234, v38, s[16:17]
	v_add_f32_e32 v37, 0xc1c00000, v36
	v_add_f32_e32 v38, 0xc2600000, v36
	v_cmp_le_f32_e64 vcc, |v37|, s76
	v_cmp_le_f32_e64 s[16:17], |v38|, s76
	v_mul_f32_e64 v37, v193, |v37|
	v_mul_f32_e64 v38, v193, |v38|
	v_fmac_f32_e32 v37, 0x3e0293ee, v32
	v_fmac_f32_e32 v38, 0x3e0293ee, v16
	v_cndmask_b32_e32 v32, v234, v37, vcc
	v_cndmask_b32_e64 v16, v234, v38, s[16:17]
	v_add_f32_e32 v37, 0xc1c80000, v36
	v_add_f32_e32 v38, 0xc2640000, v36
	v_cmp_le_f32_e64 vcc, |v37|, s76
	v_cmp_le_f32_e64 s[16:17], |v38|, s76
	v_mul_f32_e64 v37, v193, |v37|
	v_mul_f32_e64 v38, v193, |v38|
	v_fmac_f32_e32 v37, 0x3e0293ee, v33
	v_fmac_f32_e32 v38, 0x3e0293ee, v17
	v_cndmask_b32_e32 v33, v234, v37, vcc
	v_cndmask_b32_e64 v17, v234, v38, s[16:17]
	v_add_f32_e32 v37, 0xc1d00000, v36
	v_add_f32_e32 v38, 0xc2680000, v36
	v_cmp_le_f32_e64 vcc, |v37|, s76
	v_cmp_le_f32_e64 s[16:17], |v38|, s76
	v_mul_f32_e64 v37, v193, |v37|
	v_mul_f32_e64 v38, v193, |v38|
	v_fmac_f32_e32 v37, 0x3e0293ee, v34
	v_fmac_f32_e32 v38, 0x3e0293ee, v18
	v_cndmask_b32_e32 v34, v234, v37, vcc
	v_cndmask_b32_e64 v18, v234, v38, s[16:17]
	v_add_f32_e32 v37, 0xc26c0000, v36
	v_add_f32_e32 v38, 0xc1d80000, v36
	v_cmp_le_f32_e64 vcc, |v37|, s76
	v_cmp_le_f32_e64 s[16:17], |v38|, s76
	v_mul_f32_e64 v37, v193, |v37|
	v_mul_f32_e64 v38, v193, |v38|
	v_fmac_f32_e32 v37, 0x3e0293ee, v19
	v_fmac_f32_e32 v38, 0x3e0293ee, v35
	v_cndmask_b32_e32 v19, v234, v37, vcc
	v_cndmask_b32_e64 v35, v234, v38, s[16:17]
	s_branch .Lam_done_0
.Lam_out_0:
	s_nop 7
	v_mov_b32_e32 v4, v234
	v_mov_b32_e32 v20, v234
	v_mov_b32_e32 v21, v234
	v_mov_b32_e32 v5, v234
	v_mov_b32_e32 v22, v234
	v_mov_b32_e32 v6, v234
	v_mov_b32_e32 v23, v234
	v_mov_b32_e32 v7, v234
	v_mov_b32_e32 v24, v234
	v_mov_b32_e32 v8, v234
	v_mov_b32_e32 v25, v234
	v_mov_b32_e32 v9, v234
	v_mov_b32_e32 v26, v234
	v_mov_b32_e32 v10, v234
	v_mov_b32_e32 v27, v234
	v_mov_b32_e32 v11, v234
	v_mov_b32_e32 v28, v234
	v_mov_b32_e32 v12, v234
	v_mov_b32_e32 v29, v234
	v_mov_b32_e32 v13, v234
	v_mov_b32_e32 v30, v234
	v_mov_b32_e32 v14, v234
	v_mov_b32_e32 v31, v234
	v_mov_b32_e32 v15, v234
	v_mov_b32_e32 v32, v234
	v_mov_b32_e32 v16, v234
	v_mov_b32_e32 v33, v234
	v_mov_b32_e32 v17, v234
	v_mov_b32_e32 v34, v234
	v_mov_b32_e32 v18, v234
	v_mov_b32_e32 v19, v234
	v_mov_b32_e32 v35, v234
.Lam_done_0:
	v_max_f32_e32 v36, v20, v21
	v_max3_f32 v36, v36, v22, v23
	v_max3_f32 v36, v36, v24, v25
	v_max3_f32 v36, v36, v26, v27
	v_max3_f32 v36, v36, v28, v29
	v_max3_f32 v36, v36, v30, v31
	v_max3_f32 v36, v36, v32, v33
	v_max3_f32 v36, v36, v34, v35
	v_max3_f32 v36, v36, v4, v5
	v_max3_f32 v36, v36, v6, v7
	v_max3_f32 v36, v36, v8, v9
	v_max3_f32 v36, v36, v10, v11
	v_max3_f32 v36, v36, v12, v13
	v_max3_f32 v36, v36, v14, v15
	v_max3_f32 v36, v36, v16, v17
	v_max3_f32 v36, v36, v18, v19
	v_mov_b32_e32 v37, v36
	s_nop 1
	v_permlane32_swap_b32_e32 v36, v37
	s_mov_b32 s16, 0xf149f2ca
	v_max3_f32 v212, v36, v37, s16
	v_sub_f32_e32 v20, v20, v212
	v_exp_f32_e32 v37, v20
	v_sub_f32_e32 v20, v21, v212
	v_exp_f32_e32 v38, v20
	v_sub_f32_e32 v20, v22, v212
	v_exp_f32_e32 v39, v20
	v_sub_f32_e32 v20, v23, v212
	v_exp_f32_e32 v23, v20
	v_sub_f32_e32 v20, v24, v212
	v_exp_f32_e32 v24, v20
	v_sub_f32_e32 v20, v25, v212
	v_add_f32_e32 v21, 0, v37
	v_exp_f32_e32 v25, v20
	v_sub_f32_e32 v20, v26, v212
	v_add_f32_e32 v21, v38, v21
	v_exp_f32_e32 v26, v20
	v_sub_f32_e32 v20, v27, v212
	v_add_f32_e32 v21, v39, v21
	v_exp_f32_e32 v27, v20
	v_sub_f32_e32 v20, v28, v212
	v_add_f32_e32 v21, v23, v21
	v_exp_f32_e32 v28, v20
	v_sub_f32_e32 v20, v29, v212
	v_add_f32_e32 v21, v24, v21
	v_exp_f32_e32 v29, v20
	v_sub_f32_e32 v20, v30, v212
	v_add_f32_e32 v21, v25, v21
	v_exp_f32_e32 v30, v20
	v_sub_f32_e32 v20, v31, v212
	v_add_f32_e32 v21, v26, v21
	v_exp_f32_e32 v31, v20
	v_sub_f32_e32 v20, v32, v212
	v_add_f32_e32 v21, v27, v21
	v_exp_f32_e32 v32, v20
	v_sub_f32_e32 v20, v33, v212
	v_add_f32_e32 v21, v28, v21
	v_exp_f32_e32 v33, v20
	v_sub_f32_e32 v20, v34, v212
	v_add_f32_e32 v21, v29, v21
	v_exp_f32_e32 v34, v20
	v_sub_f32_e32 v20, v35, v212
	v_add_f32_e32 v21, v30, v21
	v_sub_f32_e32 v4, v4, v212
	v_exp_f32_e32 v35, v20
	v_add_f32_e32 v21, v31, v21
	v_sub_f32_e32 v5, v5, v212
	v_exp_f32_e32 v4, v4
	v_add_f32_e32 v21, v32, v21
	v_sub_f32_e32 v6, v6, v212
	v_exp_f32_e32 v5, v5
	v_add_f32_e32 v21, v33, v21
	v_sub_f32_e32 v7, v7, v212
	v_exp_f32_e32 v6, v6
	v_add_f32_e32 v21, v34, v21
	v_sub_f32_e32 v8, v8, v212
	v_exp_f32_e32 v7, v7
	v_add_f32_e32 v21, v35, v21
	v_sub_f32_e32 v9, v9, v212
	v_exp_f32_e32 v8, v8
	v_add_f32_e32 v21, v4, v21
	v_sub_f32_e32 v10, v10, v212
	v_exp_f32_e32 v9, v9
	v_add_f32_e32 v21, v5, v21
	v_sub_f32_e32 v11, v11, v212
	v_exp_f32_e32 v10, v10
	v_add_f32_e32 v21, v6, v21
	v_sub_f32_e32 v12, v12, v212
	v_exp_f32_e32 v11, v11
	v_add_f32_e32 v21, v7, v21
	v_sub_f32_e32 v13, v13, v212
	v_exp_f32_e32 v12, v12
	v_add_f32_e32 v21, v8, v21
	v_sub_f32_e32 v14, v14, v212
	v_exp_f32_e32 v13, v13
	v_add_f32_e32 v21, v9, v21
	v_sub_f32_e32 v15, v15, v212
	v_exp_f32_e32 v14, v14
	v_add_f32_e32 v21, v10, v21
	v_sub_f32_e32 v16, v16, v212
	v_exp_f32_e32 v15, v15
	v_add_f32_e32 v21, v11, v21
	v_sub_f32_e32 v17, v17, v212
	v_exp_f32_e32 v16, v16
	v_add_f32_e32 v21, v12, v21
	v_sub_f32_e32 v18, v18, v212
	v_exp_f32_e32 v17, v17
	v_add_f32_e32 v21, v13, v21
	v_sub_f32_e32 v19, v19, v212
	v_exp_f32_e32 v18, v18
	v_add_f32_e32 v21, v14, v21
	v_exp_f32_e32 v19, v19
	v_add_f32_e32 v21, v15, v21
	v_sub_f32_e32 v36, 0xf149f2ca, v212
	v_add_f32_e32 v21, v16, v21
	v_exp_f32_e32 v20, v36
	v_add_f32_e32 v21, v17, v21
	v_add_f32_e32 v21, v18, v21
	v_add_f32_e32 v21, v19, v21
	v_mov_b32_e32 v22, v21
	s_nop 1
	v_permlane32_swap_b32_e32 v21, v22
	v_cmp_gt_f32_e32 vcc, 1.0, v20
	v_cvt_pk_bf16_f32 v82, v37, v38
	v_cvt_pk_bf16_f32 v83, v39, v23
	v_cvt_pk_bf16_f32 v84, v24, v25
	v_cvt_pk_bf16_f32 v85, v26, v27
	v_cvt_pk_bf16_f32 v78, v28, v29
	v_cvt_pk_bf16_f32 v79, v30, v31
	v_cvt_pk_bf16_f32 v80, v32, v33
	v_cvt_pk_bf16_f32 v81, v34, v35
	v_cvt_pk_bf16_f32 v74, v4, v5
	v_cvt_pk_bf16_f32 v75, v6, v7
	v_cvt_pk_bf16_f32 v76, v8, v9
	v_cvt_pk_bf16_f32 v77, v10, v11
	v_cvt_pk_bf16_f32 v70, v12, v13
	v_cvt_pk_bf16_f32 v71, v14, v15
	v_cvt_pk_bf16_f32 v72, v16, v17
	v_cvt_pk_bf16_f32 v73, v18, v19
	s_cbranch_vccz .LBB0_559
	s_and_saveexec_b64 s[22:23], s[38:39]
	ds_write_b32 v191, v20 offset:128
	s_or_b64 exec, exec, s[22:23]
	s_waitcnt lgkmcnt(0)
	v_lshl_add_u32 v12, v185, 2, s44
	ds_read_b128 v[4:7], v12 offset:224
	ds_read_b128 v[8:11], v12 offset:192
	ds_read_b128 v[24:27], v12 offset:160
	ds_read_b128 v[28:31], v12 offset:128
	s_waitcnt lgkmcnt(3)
	v_pk_mul_f32 v[18:19], v[6:7], 0 op_sel_hi:[1,0]
	s_waitcnt lgkmcnt(2)
	v_pk_mul_f32 v[14:15], v[10:11], 0 op_sel_hi:[1,0]
	s_waitcnt lgkmcnt(1)
	v_pk_mul_f32 v[10:11], v[26:27], 0 op_sel_hi:[1,0]
	s_waitcnt lgkmcnt(0)
	v_pk_mul_f32 v[6:7], v[30:31], 0 op_sel_hi:[1,0]
	v_pk_mul_f32 v[16:17], v[4:5], 0 op_sel_hi:[1,0]
	v_pk_mul_f32 v[12:13], v[8:9], 0 op_sel_hi:[1,0]
	v_pk_mul_f32 v[8:9], v[24:25], 0 op_sel_hi:[1,0]
	v_pk_mul_f32 v[4:5], v[28:29], 0 op_sel_hi:[1,0]
	s_branch .LBB0_560

.LBB0_561:
	v_add_u32_e32 v210, 0x80, v86
	v_add_u32_e32 v69, 0xa0, v86
	v_min_i32_e32 v70, s3, v210
	v_cmp_lt_i32_e32 vcc, -1, v210
	s_movk_i32 s16, 0xffdf
	v_min_i32_e32 v69, s3, v69
	v_cndmask_b32_e32 v70, 0, v70, vcc
	v_cmp_lt_i32_e32 vcc, s16, v210
	v_ashrrev_i32_e32 v71, 31, v70
	v_lshlrev_b64 v[70:71], s18, v[70:71]
	v_cndmask_b32_e32 v72, 0, v69, vcc
	v_ashrrev_i32_e32 v73, 31, v72
	v_lshlrev_b64 v[72:73], s18, v[72:73]
	v_lshl_add_u64 v[70:71], v[70:71], 0, v[2:3]
	v_lshl_add_u64 v[72:73], v[72:73], 0, v[2:3]
	v_lshlrev_b64 v[70:71], 1, v[70:71]
	v_lshlrev_b64 v[72:73], 1, v[72:73]
	v_lshl_add_u64 v[74:75], s[12:13], 0, v[70:71]
	v_lshl_add_u64 v[76:77], s[12:13], 0, v[72:73]
	v_lshl_add_u64 v[72:73], s[10:11], 0, v[72:73]
	s_waitcnt vmcnt(4)
	ds_write_b128 v196, v[134:137] offset:16384
	ds_write_b128 v197, v[138:141] offset:16384
	ds_write_b128 v198, v[142:145] offset:49152
	ds_write_b128 v199, v[146:149] offset:49152
	s_waitcnt lgkmcnt(0)
	s_barrier
	global_load_dwordx4 v[142:145], v[74:75], off
	global_load_dwordx4 v[146:149], v[76:77], off
	v_lshl_add_u64 v[70:71], s[10:11], 0, v[70:71]
	global_load_dwordx4 v[158:161], v[72:73], off
	global_load_dwordx4 v[162:165], v[70:71], off
	s_cmp_lg_u32 0, -1
	s_cselect_b32 s16, 0, 0
	s_addk_i32 s16, 0x4000
	s_add_i32 s17, s46, 1
	s_cmp_gt_u32 s17, 2
	v_add_u32_e32 v69, s16, v87
	s_cbranch_scc1 .LBB0_567
	ds_read_b128 v[70:73], v207 offset:49152
	ds_read_b128 v[74:77], v207 offset:57344
	ds_read_b128 v[134:137], v206 offset:49152
	ds_read_b128 v[138:141], v206 offset:57344
	s_waitcnt lgkmcnt(3)
	v_mfma_f32_32x32x16_bf16 v[86:101], v[70:73], v[110:113], 0
	s_waitcnt lgkmcnt(2)
	v_mfma_f32_32x32x16_bf16 v[70:85], v[74:77], v[110:113], 0
	ds_read_b128 v[214:217], v205 offset:49152
	ds_read_b128 v[218:221], v205 offset:57344
	s_waitcnt lgkmcnt(3)
	v_mfma_f32_32x32x16_bf16 v[86:101], v[134:137], v[130:133], v[86:101]
	s_waitcnt lgkmcnt(2)
	v_mfma_f32_32x32x16_bf16 v[70:85], v[138:141], v[130:133], v[70:85]
	ds_read_b128 v[134:137], v204 offset:49152
	ds_read_b128 v[138:141], v204 offset:57344
	s_waitcnt lgkmcnt(3)
	v_mfma_f32_32x32x16_bf16 v[86:101], v[214:217], v[126:129], v[86:101]
	s_waitcnt lgkmcnt(2)
	v_mfma_f32_32x32x16_bf16 v[70:85], v[218:221], v[126:129], v[70:85]
	ds_read_b128 v[214:217], v203 offset:49152
	ds_read_b128 v[218:221], v203 offset:57344
	s_waitcnt lgkmcnt(3)
	v_mfma_f32_32x32x16_bf16 v[86:101], v[134:137], v[122:125], v[86:101]
	s_waitcnt lgkmcnt(2)
	v_mfma_f32_32x32x16_bf16 v[70:85], v[138:141], v[122:125], v[70:85]
	ds_read_b128 v[134:137], v202 offset:49152
	ds_read_b128 v[138:141], v202 offset:57344
	s_waitcnt lgkmcnt(3)
	v_mfma_f32_32x32x16_bf16 v[86:101], v[214:217], v[118:121], v[86:101]
	s_waitcnt lgkmcnt(2)
	v_mfma_f32_32x32x16_bf16 v[70:85], v[218:221], v[118:121], v[70:85]
	ds_read_b128 v[214:217], v201 offset:49152
	ds_read_b128 v[218:221], v201 offset:57344
	s_waitcnt lgkmcnt(3)
	v_mfma_f32_32x32x16_bf16 v[86:101], v[134:137], v[114:117], v[86:101]
	s_waitcnt lgkmcnt(2)
	v_mfma_f32_32x32x16_bf16 v[70:85], v[138:141], v[114:117], v[70:85]
	ds_read_b128 v[134:137], v200 offset:49152
	ds_read_b128 v[138:141], v200 offset:57344
	s_waitcnt lgkmcnt(3)
	v_mfma_f32_32x32x16_bf16 v[86:101], v[214:217], v[106:109], v[86:101]
	s_waitcnt lgkmcnt(2)
	v_mfma_f32_32x32x16_bf16 v[70:85], v[218:221], v[106:109], v[70:85]
	s_waitcnt lgkmcnt(1)
	v_mfma_f32_32x32x16_bf16 v[86:101], v[134:137], v[102:105], v[86:101]
	s_waitcnt lgkmcnt(0)
	v_mfma_f32_32x32x16_bf16 v[70:85], v[138:141], v[102:105], v[70:85]
	v_add_u32_e32 v134, 64, v194
	v_sub_u32_e32 v135, v192, v134
	v_cvt_f32_i32_e32 v135, v135
	v_readfirstlane_b32 s40, v134
	s_add_i32 s41, s40, 64
	s_cmp_lt_i32 s40, 0
	s_cbranch_scc1 .Lam_out_1
	s_cmp_gt_i32 s41, s45
	s_cbranch_scc1 .Lam_out_1
	v_mov_b32_e32 v134, v135
	v_add_f32_e32 v136, 0xc2000000, v135
	v_cmp_le_f32_e64 vcc, |v134|, s76
	v_cmp_le_f32_e64 s[16:17], |v136|, s76
	v_mul_f32_e64 v134, v193, |v134|
	v_mul_f32_e64 v136, v193, |v136|
	v_fmac_f32_e32 v134, 0x3e0293ee, v86
	v_fmac_f32_e32 v136, 0x3e0293ee, v70
	v_cndmask_b32_e32 v86, v234, v134, vcc
	v_cndmask_b32_e64 v70, v234, v136, s[16:17]
	v_add_f32_e32 v134, -1.0, v135
	v_add_f32_e32 v136, 0xc2040000, v135
	v_cmp_le_f32_e64 vcc, |v134|, s76
	v_cmp_le_f32_e64 s[16:17], |v136|, s76
	v_mul_f32_e64 v134, v193, |v134|
	v_mul_f32_e64 v136, v193, |v136|
	v_fmac_f32_e32 v134, 0x3e0293ee, v87
	v_fmac_f32_e32 v136, 0x3e0293ee, v71
	v_cndmask_b32_e32 v87, v234, v134, vcc
	v_cndmask_b32_e64 v71, v234, v136, s[16:17]
	v_add_f32_e32 v134, -2.0, v135
	v_add_f32_e32 v136, 0xc2080000, v135
	v_cmp_le_f32_e64 vcc, |v134|, s76
	v_cmp_le_f32_e64 s[16:17], |v136|, s76
	v_mul_f32_e64 v134, v193, |v134|
	v_mul_f32_e64 v136, v193, |v136|
	v_fmac_f32_e32 v134, 0x3e0293ee, v88
	v_fmac_f32_e32 v136, 0x3e0293ee, v72
	v_cndmask_b32_e32 v88, v234, v134, vcc
	v_cndmask_b32_e64 v72, v234, v136, s[16:17]
	v_add_f32_e32 v134, 0xc0400000, v135
	v_add_f32_e32 v136, 0xc20c0000, v135
	v_cmp_le_f32_e64 vcc, |v134|, s76
	v_cmp_le_f32_e64 s[16:17], |v136|, s76
	v_mul_f32_e64 v134, v193, |v134|
	v_mul_f32_e64 v136, v193, |v136|
	v_fmac_f32_e32 v134, 0x3e0293ee, v89
	v_fmac_f32_e32 v136, 0x3e0293ee, v73
	v_cndmask_b32_e32 v89, v234, v134, vcc
	v_cndmask_b32_e64 v73, v234, v136, s[16:17]
	v_add_f32_e32 v134, 0xc1000000, v135
	v_add_f32_e32 v136, 0xc2200000, v135
	v_cmp_le_f32_e64 vcc, |v134|, s76
	v_cmp_le_f32_e64 s[16:17], |v136|, s76
	v_mul_f32_e64 v134, v193, |v134|
	v_mul_f32_e64 v136, v193, |v136|
	v_fmac_f32_e32 v134, 0x3e0293ee, v90
	v_fmac_f32_e32 v136, 0x3e0293ee, v74
	v_cndmask_b32_e32 v90, v234, v134, vcc
	v_cndmask_b32_e64 v74, v234, v136, s[16:17]
	v_add_f32_e32 v134, 0xc1100000, v135
	v_add_f32_e32 v136, 0xc2240000, v135
	v_cmp_le_f32_e64 vcc, |v134|, s76
	v_cmp_le_f32_e64 s[16:17], |v136|, s76
	v_mul_f32_e64 v134, v193, |v134|
	v_mul_f32_e64 v136, v193, |v136|
	v_fmac_f32_e32 v134, 0x3e0293ee, v91
	v_fmac_f32_e32 v136, 0x3e0293ee, v75
	v_cndmask_b32_e32 v91, v234, v134, vcc
	v_cndmask_b32_e64 v75, v234, v136, s[16:17]
	v_add_f32_e32 v134, 0xc1200000, v135
	v_add_f32_e32 v136, 0xc2280000, v135
	v_cmp_le_f32_e64 vcc, |v134|, s76
	v_cmp_le_f32_e64 s[16:17], |v136|, s76
	v_mul_f32_e64 v134, v193, |v134|
	v_mul_f32_e64 v136, v193, |v136|
	v_fmac_f32_e32 v134, 0x3e0293ee, v92
	v_fmac_f32_e32 v136, 0x3e0293ee, v76
	v_cndmask_b32_e32 v92, v234, v134, vcc
	v_cndmask_b32_e64 v76, v234, v136, s[16:17]
	v_add_f32_e32 v134, 0xc1300000, v135
	v_add_f32_e32 v136, 0xc22c0000, v135
	v_cmp_le_f32_e64 vcc, |v134|, s76
	v_cmp_le_f32_e64 s[16:17], |v136|, s76
	v_mul_f32_e64 v134, v193, |v134|
	v_mul_f32_e64 v136, v193, |v136|
	v_fmac_f32_e32 v134, 0x3e0293ee, v93
	v_fmac_f32_e32 v136, 0x3e0293ee, v77
	v_cndmask_b32_e32 v93, v234, v134, vcc
	v_cndmask_b32_e64 v77, v234, v136, s[16:17]
	v_add_f32_e32 v134, 0xc1800000, v135
	v_add_f32_e32 v136, 0xc2400000, v135
	v_cmp_le_f32_e64 vcc, |v134|, s76
	v_cmp_le_f32_e64 s[16:17], |v136|, s76
	v_mul_f32_e64 v134, v193, |v134|
	v_mul_f32_e64 v136, v193, |v136|
	v_fmac_f32_e32 v134, 0x3e0293ee, v94
	v_fmac_f32_e32 v136, 0x3e0293ee, v78
	v_cndmask_b32_e32 v94, v234, v134, vcc
	v_cndmask_b32_e64 v78, v234, v136, s[16:17]
	v_add_f32_e32 v134, 0xc1880000, v135
	v_add_f32_e32 v136, 0xc2440000, v135
	v_cmp_le_f32_e64 vcc, |v134|, s76
	v_cmp_le_f32_e64 s[16:17], |v136|, s76
	v_mul_f32_e64 v134, v193, |v134|
	v_mul_f32_e64 v136, v193, |v136|
	v_fmac_f32_e32 v134, 0x3e0293ee, v95
	v_fmac_f32_e32 v136, 0x3e0293ee, v79
	v_cndmask_b32_e32 v95, v234, v134, vcc
	v_cndmask_b32_e64 v79, v234, v136, s[16:17]
	v_add_f32_e32 v134, 0xc1900000, v135
	v_add_f32_e32 v136, 0xc2480000, v135
	v_cmp_le_f32_e64 vcc, |v134|, s76
	v_cmp_le_f32_e64 s[16:17], |v136|, s76
	v_mul_f32_e64 v134, v193, |v134|
	v_mul_f32_e64 v136, v193, |v136|
	v_fmac_f32_e32 v134, 0x3e0293ee, v96
	v_fmac_f32_e32 v136, 0x3e0293ee, v80
	v_cndmask_b32_e32 v96, v234, v134, vcc
	v_cndmask_b32_e64 v80, v234, v136, s[16:17]
	v_add_f32_e32 v134, 0xc1980000, v135
	v_add_f32_e32 v136, 0xc24c0000, v135
	v_cmp_le_f32_e64 vcc, |v134|, s76
	v_cmp_le_f32_e64 s[16:17], |v136|, s76
	v_mul_f32_e64 v134, v193, |v134|
	v_mul_f32_e64 v136, v193, |v136|
	v_fmac_f32_e32 v134, 0x3e0293ee, v97
	v_fmac_f32_e32 v136, 0x3e0293ee, v81
	v_cndmask_b32_e32 v97, v234, v134, vcc
	v_cndmask_b32_e64 v81, v234, v136, s[16:17]
	v_add_f32_e32 v134, 0xc1c00000, v135
	v_add_f32_e32 v136, 0xc2600000, v135
	v_cmp_le_f32_e64 vcc, |v134|, s76
	v_cmp_le_f32_e64 s[16:17], |v136|, s76
	v_mul_f32_e64 v134, v193, |v134|
	v_mul_f32_e64 v136, v193, |v136|
	v_fmac_f32_e32 v134, 0x3e0293ee, v98
	v_fmac_f32_e32 v136, 0x3e0293ee, v82
	v_cndmask_b32_e32 v98, v234, v134, vcc
	v_cndmask_b32_e64 v82, v234, v136, s[16:17]
	v_add_f32_e32 v134, 0xc1c80000, v135
	v_add_f32_e32 v136, 0xc2640000, v135
	v_cmp_le_f32_e64 vcc, |v134|, s76
	v_cmp_le_f32_e64 s[16:17], |v136|, s76
	v_mul_f32_e64 v134, v193, |v134|
	v_mul_f32_e64 v136, v193, |v136|
	v_fmac_f32_e32 v134, 0x3e0293ee, v99
	v_fmac_f32_e32 v136, 0x3e0293ee, v83
	v_cndmask_b32_e32 v99, v234, v134, vcc
	v_cndmask_b32_e64 v83, v234, v136, s[16:17]
	v_add_f32_e32 v134, 0xc1d00000, v135
	v_add_f32_e32 v136, 0xc2680000, v135
	v_cmp_le_f32_e64 vcc, |v134|, s76
	v_cmp_le_f32_e64 s[16:17], |v136|, s76
	v_mul_f32_e64 v134, v193, |v134|
	v_mul_f32_e64 v136, v193, |v136|
	v_fmac_f32_e32 v134, 0x3e0293ee, v100
	v_fmac_f32_e32 v136, 0x3e0293ee, v84
	v_cndmask_b32_e32 v100, v234, v134, vcc
	v_cndmask_b32_e64 v84, v234, v136, s[16:17]
	v_add_f32_e32 v134, 0xc1d80000, v135
	v_add_f32_e32 v136, 0xc26c0000, v135
	v_cmp_le_f32_e64 vcc, |v134|, s76
	v_cmp_le_f32_e64 s[16:17], |v136|, s76
	v_mul_f32_e64 v134, v193, |v134|
	v_mul_f32_e64 v136, v193, |v136|
	v_fmac_f32_e32 v134, 0x3e0293ee, v101
	v_fmac_f32_e32 v136, 0x3e0293ee, v85
	v_cndmask_b32_e32 v101, v234, v134, vcc
	v_cndmask_b32_e64 v85, v234, v136, s[16:17]
	s_branch .Lam_done_1
.Lam_out_1:
	s_nop 7
	v_mov_b32_e32 v86, v234
	v_mov_b32_e32 v70, v234
	v_mov_b32_e32 v87, v234
	v_mov_b32_e32 v71, v234
	v_mov_b32_e32 v88, v234
	v_mov_b32_e32 v72, v234
	v_mov_b32_e32 v89, v234
	v_mov_b32_e32 v73, v234
	v_mov_b32_e32 v90, v234
	v_mov_b32_e32 v74, v234
	v_mov_b32_e32 v91, v234
	v_mov_b32_e32 v75, v234
	v_mov_b32_e32 v92, v234
	v_mov_b32_e32 v76, v234
	v_mov_b32_e32 v93, v234
	v_mov_b32_e32 v77, v234
	v_mov_b32_e32 v94, v234
	v_mov_b32_e32 v78, v234
	v_mov_b32_e32 v95, v234
	v_mov_b32_e32 v79, v234
	v_mov_b32_e32 v96, v234
	v_mov_b32_e32 v80, v234
	v_mov_b32_e32 v97, v234
	v_mov_b32_e32 v81, v234
	v_mov_b32_e32 v98, v234
	v_mov_b32_e32 v82, v234
	v_mov_b32_e32 v99, v234
	v_mov_b32_e32 v83, v234
	v_mov_b32_e32 v100, v234
	v_mov_b32_e32 v84, v234
	v_mov_b32_e32 v101, v234
	v_mov_b32_e32 v85, v234
.Lam_done_1:
	v_max_f32_e32 v134, v86, v87
	v_max3_f32 v134, v134, v88, v89
	v_max3_f32 v134, v134, v90, v91
	v_max3_f32 v134, v134, v92, v93
	v_max3_f32 v134, v134, v94, v95
	v_max3_f32 v134, v134, v96, v97
	v_max3_f32 v134, v134, v98, v99
	v_max3_f32 v134, v134, v100, v101
	v_max3_f32 v134, v134, v70, v71
	v_max3_f32 v134, v134, v72, v73
	v_max3_f32 v134, v134, v74, v75
	v_max3_f32 v134, v134, v76, v77
	v_max3_f32 v134, v134, v78, v79
	v_max3_f32 v134, v134, v80, v81
	v_max3_f32 v134, v134, v82, v83
	v_max3_f32 v134, v134, v84, v85
	v_mov_b32_e32 v135, v134
	s_nop 1
	v_permlane32_swap_b32_e32 v134, v135
	v_max3_f32 v211, v212, v134, v135
	v_sub_f32_e32 v86, v86, v211
	v_exp_f32_e32 v135, v86
	v_sub_f32_e32 v86, v87, v211
	v_exp_f32_e32 v136, v86
	v_sub_f32_e32 v86, v88, v211
	v_exp_f32_e32 v137, v86
	v_sub_f32_e32 v86, v89, v211
	v_exp_f32_e32 v89, v86
	v_sub_f32_e32 v86, v90, v211
	v_exp_f32_e32 v90, v86
	v_sub_f32_e32 v86, v91, v211
	v_exp_f32_e32 v91, v86
	v_sub_f32_e32 v86, v92, v211
	v_exp_f32_e32 v92, v86
	v_sub_f32_e32 v86, v93, v211
	v_exp_f32_e32 v93, v86
	v_sub_f32_e32 v86, v94, v211
	v_exp_f32_e32 v94, v86
	v_sub_f32_e32 v86, v95, v211
	v_exp_f32_e32 v95, v86
	v_sub_f32_e32 v86, v96, v211
	v_exp_f32_e32 v96, v86
	v_sub_f32_e32 v86, v97, v211
	v_exp_f32_e32 v97, v86
	v_sub_f32_e32 v86, v98, v211
	v_exp_f32_e32 v98, v86
	v_sub_f32_e32 v86, v99, v211
	v_exp_f32_e32 v99, v86
	v_sub_f32_e32 v86, v100, v211
	v_sub_f32_e32 v134, v212, v211
	v_sub_f32_e32 v74, v74, v211
	v_exp_f32_e32 v100, v86
	v_sub_f32_e32 v86, v101, v211
	v_exp_f32_e32 v101, v86
	v_exp_f32_e32 v86, v134
	v_exp_f32_e32 v134, v74
	v_add_f32_e32 v74, 0, v135
	v_add_f32_e32 v74, v136, v74
	v_add_f32_e32 v74, v137, v74
	v_add_f32_e32 v74, v89, v74
	v_add_f32_e32 v74, v90, v74
	v_add_f32_e32 v74, v91, v74
	v_add_f32_e32 v74, v92, v74
	v_add_f32_e32 v74, v93, v74
	v_add_f32_e32 v74, v94, v74
	v_add_f32_e32 v74, v95, v74
	v_add_f32_e32 v74, v96, v74
	v_sub_f32_e32 v70, v70, v211
	v_add_f32_e32 v74, v97, v74
	v_sub_f32_e32 v71, v71, v211
	v_exp_f32_e32 v70, v70
	v_add_f32_e32 v74, v98, v74
	v_sub_f32_e32 v72, v72, v211
	v_exp_f32_e32 v71, v71
	v_add_f32_e32 v74, v99, v74
	v_sub_f32_e32 v73, v73, v211
	v_exp_f32_e32 v72, v72
	v_add_f32_e32 v74, v100, v74
	v_exp_f32_e32 v73, v73
	v_add_f32_e32 v74, v101, v74
	v_sub_f32_e32 v75, v75, v211
	v_add_f32_e32 v74, v70, v74
	v_sub_f32_e32 v76, v76, v211
	v_exp_f32_e32 v138, v75
	v_add_f32_e32 v74, v71, v74
	v_sub_f32_e32 v77, v77, v211
	v_exp_f32_e32 v139, v76
	v_add_f32_e32 v74, v72, v74
	v_sub_f32_e32 v78, v78, v211
	v_exp_f32_e32 v77, v77
	v_add_f32_e32 v74, v73, v74
	v_sub_f32_e32 v79, v79, v211
	v_exp_f32_e32 v140, v78
	v_add_f32_e32 v74, v134, v74
	v_sub_f32_e32 v80, v80, v211
	v_exp_f32_e32 v141, v79
	v_add_f32_e32 v74, v138, v74
	v_sub_f32_e32 v81, v81, v211
	v_exp_f32_e32 v174, v80
	v_add_f32_e32 v74, v139, v74
	v_sub_f32_e32 v82, v82, v211
	v_exp_f32_e32 v175, v81
	v_add_f32_e32 v74, v77, v74
	v_sub_f32_e32 v83, v83, v211
	v_exp_f32_e32 v176, v82
	v_add_f32_e32 v74, v140, v74
	v_sub_f32_e32 v84, v84, v211
	v_exp_f32_e32 v177, v83
	v_add_f32_e32 v74, v141, v74
	v_sub_f32_e32 v85, v85, v211
	v_exp_f32_e32 v178, v84
	v_add_f32_e32 v74, v174, v74
	v_exp_f32_e32 v179, v85
	v_add_f32_e32 v74, v175, v74
	v_add_f32_e32 v74, v176, v74
	v_add_f32_e32 v74, v177, v74
	v_add_f32_e32 v74, v178, v74
	v_add_f32_e32 v87, v179, v74
	v_mov_b32_e32 v88, v87
	s_nop 1
	v_permlane32_swap_b32_e32 v87, v88
	v_cmp_gt_f32_e32 vcc, 1.0, v86
	v_cvt_pk_bf16_f32 v82, v135, v136
	v_cvt_pk_bf16_f32 v83, v137, v89
	v_cvt_pk_bf16_f32 v84, v90, v91
	v_cvt_pk_bf16_f32 v85, v92, v93
	v_cvt_pk_bf16_f32 v78, v94, v95
	v_cvt_pk_bf16_f32 v79, v96, v97
	v_cvt_pk_bf16_f32 v80, v98, v99
	v_cvt_pk_bf16_f32 v81, v100, v101
	v_cvt_pk_bf16_f32 v74, v70, v71
	v_cvt_pk_bf16_f32 v75, v72, v73
	v_cvt_pk_bf16_f32 v76, v134, v138
	v_cvt_pk_bf16_f32 v77, v139, v77
	v_cvt_pk_bf16_f32 v70, v140, v141
	v_cvt_pk_bf16_f32 v71, v174, v175
	v_cvt_pk_bf16_f32 v72, v176, v177
	v_cvt_pk_bf16_f32 v73, v178, v179
	s_cbranch_vccz .LBB0_566
	s_and_saveexec_b64 s[22:23], s[38:39]
	ds_write_b32 v191, v86 offset:128
	s_or_b64 exec, exec, s[22:23]
	s_waitcnt lgkmcnt(0)
	v_lshl_add_u32 v89, v185, 2, s44
	ds_read_b128 v[90:93], v89 offset:224
	ds_read_b128 v[94:97], v89 offset:192
	ds_read_b128 v[98:101], v89 offset:160
	ds_read_b128 v[134:137], v89 offset:128
	s_waitcnt lgkmcnt(3)
	v_pk_mul_f32 v[34:35], v[34:35], v[92:93]
	s_waitcnt lgkmcnt(2)
	v_pk_mul_f32 v[30:31], v[30:31], v[96:97]
	s_waitcnt lgkmcnt(1)
	v_pk_mul_f32 v[26:27], v[26:27], v[100:101]
	s_waitcnt lgkmcnt(0)
	v_pk_mul_f32 v[22:23], v[22:23], v[136:137]
	v_pk_mul_f32 v[32:33], v[32:33], v[90:91]
	v_pk_mul_f32 v[28:29], v[28:29], v[94:95]
	v_pk_mul_f32 v[24:25], v[24:25], v[98:99]
	v_pk_mul_f32 v[20:21], v[20:21], v[134:135]
	v_pk_mul_f32 v[50:51], v[50:51], v[92:93]
	v_pk_mul_f32 v[46:47], v[46:47], v[96:97]
	v_pk_mul_f32 v[42:43], v[42:43], v[100:101]
	v_pk_mul_f32 v[38:39], v[38:39], v[136:137]
	v_pk_mul_f32 v[48:49], v[48:49], v[90:91]
	v_pk_mul_f32 v[44:45], v[44:45], v[94:95]
	v_pk_mul_f32 v[40:41], v[40:41], v[98:99]
	v_pk_mul_f32 v[36:37], v[36:37], v[134:135]
	v_pk_mul_f32 v[66:67], v[66:67], v[92:93]
	v_pk_mul_f32 v[62:63], v[62:63], v[96:97]
	v_pk_mul_f32 v[58:59], v[58:59], v[100:101]
	v_pk_mul_f32 v[54:55], v[54:55], v[136:137]
	v_pk_mul_f32 v[64:65], v[64:65], v[90:91]
	v_pk_mul_f32 v[60:61], v[60:61], v[94:95]
	v_pk_mul_f32 v[56:57], v[56:57], v[98:99]
	v_pk_mul_f32 v[52:53], v[52:53], v[134:135]
	v_pk_mul_f32 v[18:19], v[18:19], v[92:93]
	v_pk_mul_f32 v[14:15], v[14:15], v[96:97]
	v_pk_mul_f32 v[10:11], v[10:11], v[100:101]
	v_pk_mul_f32 v[6:7], v[6:7], v[136:137]
	v_pk_mul_f32 v[16:17], v[16:17], v[90:91]
	v_pk_mul_f32 v[12:13], v[12:13], v[94:95]
	v_pk_mul_f32 v[8:9], v[8:9], v[98:99]
	v_pk_mul_f32 v[4:5], v[4:5], v[134:135]

.LBB0_568:
	v_add_u32_e32 v70, 0x100, v209
	s_movk_i32 s16, 0xfeff
	v_add_u32_e32 v72, 0x120, v209
	v_min_i32_e32 v70, s3, v70
	v_cmp_lt_i32_e32 vcc, s16, v209
	s_movk_i32 s16, 0xfedf
	v_min_i32_e32 v72, s3, v72
	v_cndmask_b32_e32 v70, 0, v70, vcc
	v_cmp_lt_i32_e32 vcc, s16, v209
	v_ashrrev_i32_e32 v71, 31, v70
	v_lshlrev_b64 v[70:71], s18, v[70:71]
	v_cndmask_b32_e32 v72, 0, v72, vcc
	v_ashrrev_i32_e32 v73, 31, v72
	v_lshlrev_b64 v[72:73], s18, v[72:73]
	v_lshl_add_u64 v[70:71], v[70:71], 0, v[2:3]
	v_lshl_add_u64 v[72:73], v[72:73], 0, v[2:3]
	v_lshlrev_b64 v[70:71], 1, v[70:71]
	v_lshlrev_b64 v[72:73], 1, v[72:73]
	v_lshl_add_u64 v[74:75], s[12:13], 0, v[70:71]
	v_lshl_add_u64 v[76:77], s[12:13], 0, v[72:73]
	v_lshl_add_u64 v[72:73], s[10:11], 0, v[72:73]
	s_waitcnt vmcnt(4)
	s_waitcnt vmcnt(7)
	ds_write_b128 v196, v[150:153]
	s_waitcnt vmcnt(6)
	ds_write_b128 v197, v[154:157]
	s_waitcnt vmcnt(4)
	ds_write_b128 v198, v[170:173] offset:32768
	ds_write_b128 v199, v[166:169] offset:32768
	s_waitcnt lgkmcnt(0)
	s_barrier
	global_load_dwordx4 v[134:137], v[74:75], off
	global_load_dwordx4 v[138:141], v[76:77], off
	v_lshl_add_u64 v[70:71], s[10:11], 0, v[70:71]
	global_load_dwordx4 v[150:153], v[72:73], off
	global_load_dwordx4 v[154:157], v[70:71], off
	s_cmp_gt_u32 s46, 2
	s_cbranch_scc1 .LBB0_574
	ds_read_b128 v[70:73], v207 offset:32768
	ds_read_b128 v[74:77], v207 offset:40960
	ds_read_b128 v[166:169], v206 offset:32768
	ds_read_b128 v[170:173], v206 offset:40960
	s_waitcnt lgkmcnt(3)
	v_mfma_f32_32x32x16_bf16 v[86:101], v[70:73], v[110:113], 0
	s_waitcnt lgkmcnt(2)
	v_mfma_f32_32x32x16_bf16 v[70:85], v[74:77], v[110:113], 0
	ds_read_b128 v[212:215], v205 offset:32768
	ds_read_b128 v[216:219], v205 offset:40960
	s_waitcnt lgkmcnt(3)
	v_mfma_f32_32x32x16_bf16 v[86:101], v[166:169], v[130:133], v[86:101]
	s_waitcnt lgkmcnt(2)
	v_mfma_f32_32x32x16_bf16 v[70:85], v[170:173], v[130:133], v[70:85]
	ds_read_b128 v[166:169], v204 offset:32768
	ds_read_b128 v[170:173], v204 offset:40960
	s_waitcnt lgkmcnt(3)
	v_mfma_f32_32x32x16_bf16 v[86:101], v[212:215], v[126:129], v[86:101]
	s_waitcnt lgkmcnt(2)
	v_mfma_f32_32x32x16_bf16 v[70:85], v[216:219], v[126:129], v[70:85]
	ds_read_b128 v[212:215], v203 offset:32768
	ds_read_b128 v[216:219], v203 offset:40960
	s_waitcnt lgkmcnt(3)
	v_mfma_f32_32x32x16_bf16 v[86:101], v[166:169], v[122:125], v[86:101]
	s_waitcnt lgkmcnt(2)
	v_mfma_f32_32x32x16_bf16 v[70:85], v[170:173], v[122:125], v[70:85]
	ds_read_b128 v[166:169], v202 offset:32768
	ds_read_b128 v[170:173], v202 offset:40960
	s_waitcnt lgkmcnt(3)
	v_mfma_f32_32x32x16_bf16 v[86:101], v[212:215], v[118:121], v[86:101]
	s_waitcnt lgkmcnt(2)
	v_mfma_f32_32x32x16_bf16 v[70:85], v[216:219], v[118:121], v[70:85]
	ds_read_b128 v[212:215], v201 offset:32768
	ds_read_b128 v[216:219], v201 offset:40960
	s_waitcnt lgkmcnt(3)
	v_mfma_f32_32x32x16_bf16 v[86:101], v[166:169], v[114:117], v[86:101]
	s_waitcnt lgkmcnt(2)
	v_mfma_f32_32x32x16_bf16 v[70:85], v[170:173], v[114:117], v[70:85]
	ds_read_b128 v[166:169], v200 offset:32768
	ds_read_b128 v[170:173], v200 offset:40960
	s_waitcnt lgkmcnt(3)
	v_mfma_f32_32x32x16_bf16 v[86:101], v[212:215], v[106:109], v[86:101]
	s_waitcnt lgkmcnt(2)
	v_mfma_f32_32x32x16_bf16 v[70:85], v[216:219], v[106:109], v[70:85]
	s_waitcnt lgkmcnt(1)
	v_mfma_f32_32x32x16_bf16 v[86:101], v[166:169], v[102:105], v[86:101]
	s_waitcnt lgkmcnt(0)
	v_mfma_f32_32x32x16_bf16 v[70:85], v[170:173], v[102:105], v[70:85]
	v_add_u32_e32 v166, 0x80, v194
	v_sub_u32_e32 v167, v192, v166
	v_cvt_f32_i32_e32 v167, v167
	v_readfirstlane_b32 s40, v166
	s_add_i32 s41, s40, 64
	s_cmp_lt_i32 s40, 0
	s_cbranch_scc1 .Lam_out_2
	s_cmp_gt_i32 s41, s45
	s_cbranch_scc1 .Lam_out_2
	v_mov_b32_e32 v166, v167
	v_add_f32_e32 v168, 0xc2000000, v167
	v_cmp_le_f32_e64 vcc, |v166|, s76
	v_cmp_le_f32_e64 s[16:17], |v168|, s76
	v_mul_f32_e64 v166, v193, |v166|
	v_mul_f32_e64 v168, v193, |v168|
	v_fmac_f32_e32 v166, 0x3e0293ee, v86
	v_fmac_f32_e32 v168, 0x3e0293ee, v70
	v_cndmask_b32_e32 v86, v234, v166, vcc
	v_cndmask_b32_e64 v70, v234, v168, s[16:17]
	v_add_f32_e32 v166, -1.0, v167
	v_add_f32_e32 v168, 0xc2040000, v167
	v_cmp_le_f32_e64 vcc, |v166|, s76
	v_cmp_le_f32_e64 s[16:17], |v168|, s76
	v_mul_f32_e64 v166, v193, |v166|
	v_mul_f32_e64 v168, v193, |v168|
	v_fmac_f32_e32 v166, 0x3e0293ee, v87
	v_fmac_f32_e32 v168, 0x3e0293ee, v71
	v_cndmask_b32_e32 v87, v234, v166, vcc
	v_cndmask_b32_e64 v71, v234, v168, s[16:17]
	v_add_f32_e32 v166, -2.0, v167
	v_add_f32_e32 v168, 0xc2080000, v167
	v_cmp_le_f32_e64 vcc, |v166|, s76
	v_cmp_le_f32_e64 s[16:17], |v168|, s76
	v_mul_f32_e64 v166, v193, |v166|
	v_mul_f32_e64 v168, v193, |v168|
	v_fmac_f32_e32 v166, 0x3e0293ee, v88
	v_fmac_f32_e32 v168, 0x3e0293ee, v72
	v_cndmask_b32_e32 v88, v234, v166, vcc
	v_cndmask_b32_e64 v72, v234, v168, s[16:17]
	v_add_f32_e32 v166, 0xc0400000, v167
	v_add_f32_e32 v168, 0xc20c0000, v167
	v_cmp_le_f32_e64 vcc, |v166|, s76
	v_cmp_le_f32_e64 s[16:17], |v168|, s76
	v_mul_f32_e64 v166, v193, |v166|
	v_mul_f32_e64 v168, v193, |v168|
	v_fmac_f32_e32 v166, 0x3e0293ee, v89
	v_fmac_f32_e32 v168, 0x3e0293ee, v73
	v_cndmask_b32_e32 v89, v234, v166, vcc
	v_cndmask_b32_e64 v73, v234, v168, s[16:17]
	v_add_f32_e32 v166, 0xc1000000, v167
	v_add_f32_e32 v168, 0xc2200000, v167
	v_cmp_le_f32_e64 vcc, |v166|, s76
	v_cmp_le_f32_e64 s[16:17], |v168|, s76
	v_mul_f32_e64 v166, v193, |v166|
	v_mul_f32_e64 v168, v193, |v168|
	v_fmac_f32_e32 v166, 0x3e0293ee, v90
	v_fmac_f32_e32 v168, 0x3e0293ee, v74
	v_cndmask_b32_e32 v90, v234, v166, vcc
	v_cndmask_b32_e64 v74, v234, v168, s[16:17]
	v_add_f32_e32 v166, 0xc1100000, v167
	v_add_f32_e32 v168, 0xc2240000, v167
	v_cmp_le_f32_e64 vcc, |v166|, s76
	v_cmp_le_f32_e64 s[16:17], |v168|, s76
	v_mul_f32_e64 v166, v193, |v166|
	v_mul_f32_e64 v168, v193, |v168|
	v_fmac_f32_e32 v166, 0x3e0293ee, v91
	v_fmac_f32_e32 v168, 0x3e0293ee, v75
	v_cndmask_b32_e32 v91, v234, v166, vcc
	v_cndmask_b32_e64 v75, v234, v168, s[16:17]
	v_add_f32_e32 v166, 0xc1200000, v167
	v_add_f32_e32 v168, 0xc2280000, v167
	v_cmp_le_f32_e64 vcc, |v166|, s76
	v_cmp_le_f32_e64 s[16:17], |v168|, s76
	v_mul_f32_e64 v166, v193, |v166|
	v_mul_f32_e64 v168, v193, |v168|
	v_fmac_f32_e32 v166, 0x3e0293ee, v92
	v_fmac_f32_e32 v168, 0x3e0293ee, v76
	v_cndmask_b32_e32 v92, v234, v166, vcc
	v_cndmask_b32_e64 v76, v234, v168, s[16:17]
	v_add_f32_e32 v166, 0xc1300000, v167
	v_add_f32_e32 v168, 0xc22c0000, v167
	v_cmp_le_f32_e64 vcc, |v166|, s76
	v_cmp_le_f32_e64 s[16:17], |v168|, s76
	v_mul_f32_e64 v166, v193, |v166|
	v_mul_f32_e64 v168, v193, |v168|
	v_fmac_f32_e32 v166, 0x3e0293ee, v93
	v_fmac_f32_e32 v168, 0x3e0293ee, v77
	v_cndmask_b32_e32 v93, v234, v166, vcc
	v_cndmask_b32_e64 v77, v234, v168, s[16:17]
	v_add_f32_e32 v166, 0xc1800000, v167
	v_add_f32_e32 v168, 0xc2400000, v167
	v_cmp_le_f32_e64 vcc, |v166|, s76
	v_cmp_le_f32_e64 s[16:17], |v168|, s76
	v_mul_f32_e64 v166, v193, |v166|
	v_mul_f32_e64 v168, v193, |v168|
	v_fmac_f32_e32 v166, 0x3e0293ee, v94
	v_fmac_f32_e32 v168, 0x3e0293ee, v78
	v_cndmask_b32_e32 v94, v234, v166, vcc
	v_cndmask_b32_e64 v78, v234, v168, s[16:17]
	v_add_f32_e32 v166, 0xc1880000, v167
	v_add_f32_e32 v168, 0xc2440000, v167
	v_cmp_le_f32_e64 vcc, |v166|, s76
	v_cmp_le_f32_e64 s[16:17], |v168|, s76
	v_mul_f32_e64 v166, v193, |v166|
	v_mul_f32_e64 v168, v193, |v168|
	v_fmac_f32_e32 v166, 0x3e0293ee, v95
	v_fmac_f32_e32 v168, 0x3e0293ee, v79
	v_cndmask_b32_e32 v95, v234, v166, vcc
	v_cndmask_b32_e64 v79, v234, v168, s[16:17]
	v_add_f32_e32 v166, 0xc1900000, v167
	v_add_f32_e32 v168, 0xc2480000, v167
	v_cmp_le_f32_e64 vcc, |v166|, s76
	v_cmp_le_f32_e64 s[16:17], |v168|, s76
	v_mul_f32_e64 v166, v193, |v166|
	v_mul_f32_e64 v168, v193, |v168|
	v_fmac_f32_e32 v166, 0x3e0293ee, v96
	v_fmac_f32_e32 v168, 0x3e0293ee, v80
	v_cndmask_b32_e32 v96, v234, v166, vcc
	v_cndmask_b32_e64 v80, v234, v168, s[16:17]
	v_add_f32_e32 v166, 0xc1980000, v167
	v_add_f32_e32 v168, 0xc24c0000, v167
	v_cmp_le_f32_e64 vcc, |v166|, s76
	v_cmp_le_f32_e64 s[16:17], |v168|, s76
	v_mul_f32_e64 v166, v193, |v166|
	v_mul_f32_e64 v168, v193, |v168|
	v_fmac_f32_e32 v166, 0x3e0293ee, v97
	v_fmac_f32_e32 v168, 0x3e0293ee, v81
	v_cndmask_b32_e32 v97, v234, v166, vcc
	v_cndmask_b32_e64 v81, v234, v168, s[16:17]
	v_add_f32_e32 v166, 0xc1c00000, v167
	v_add_f32_e32 v168, 0xc2600000, v167
	v_cmp_le_f32_e64 vcc, |v166|, s76
	v_cmp_le_f32_e64 s[16:17], |v168|, s76
	v_mul_f32_e64 v166, v193, |v166|
	v_mul_f32_e64 v168, v193, |v168|
	v_fmac_f32_e32 v166, 0x3e0293ee, v98
	v_fmac_f32_e32 v168, 0x3e0293ee, v82
	v_cndmask_b32_e32 v98, v234, v166, vcc
	v_cndmask_b32_e64 v82, v234, v168, s[16:17]
	v_add_f32_e32 v166, 0xc1c80000, v167
	v_add_f32_e32 v168, 0xc2640000, v167
	v_cmp_le_f32_e64 vcc, |v166|, s76
	v_cmp_le_f32_e64 s[16:17], |v168|, s76
	v_mul_f32_e64 v166, v193, |v166|
	v_mul_f32_e64 v168, v193, |v168|
	v_fmac_f32_e32 v166, 0x3e0293ee, v99
	v_fmac_f32_e32 v168, 0x3e0293ee, v83
	v_cndmask_b32_e32 v99, v234, v166, vcc
	v_cndmask_b32_e64 v83, v234, v168, s[16:17]
	v_add_f32_e32 v166, 0xc1d00000, v167
	v_add_f32_e32 v168, 0xc2680000, v167
	v_cmp_le_f32_e64 vcc, |v166|, s76
	v_cmp_le_f32_e64 s[16:17], |v168|, s76
	v_mul_f32_e64 v166, v193, |v166|
	v_mul_f32_e64 v168, v193, |v168|
	v_fmac_f32_e32 v166, 0x3e0293ee, v100
	v_fmac_f32_e32 v168, 0x3e0293ee, v84
	v_cndmask_b32_e32 v100, v234, v166, vcc
	v_cndmask_b32_e64 v84, v234, v168, s[16:17]
	v_add_f32_e32 v166, 0xc1d80000, v167
	v_add_f32_e32 v168, 0xc26c0000, v167
	v_cmp_le_f32_e64 vcc, |v166|, s76
	v_cmp_le_f32_e64 s[16:17], |v168|, s76
	v_mul_f32_e64 v166, v193, |v166|
	v_mul_f32_e64 v168, v193, |v168|
	v_fmac_f32_e32 v166, 0x3e0293ee, v101
	v_fmac_f32_e32 v168, 0x3e0293ee, v85
	v_cndmask_b32_e32 v101, v234, v166, vcc
	v_cndmask_b32_e64 v85, v234, v168, s[16:17]
	s_branch .Lam_done_2

.Lam_done_2:
	v_max_f32_e32 v166, v86, v87
	v_max3_f32 v166, v166, v88, v89
	v_max3_f32 v166, v166, v90, v91
	v_max3_f32 v166, v166, v92, v93
	v_max3_f32 v166, v166, v94, v95
	v_max3_f32 v166, v166, v96, v97
	v_max3_f32 v166, v166, v98, v99
	v_max3_f32 v166, v166, v100, v101
	v_max3_f32 v166, v166, v70, v71
	v_max3_f32 v166, v166, v72, v73
	v_max3_f32 v166, v166, v74, v75
	v_max3_f32 v166, v166, v76, v77
	v_max3_f32 v166, v166, v78, v79
	v_max3_f32 v166, v166, v80, v81
	v_max3_f32 v166, v166, v82, v83
	v_max3_f32 v166, v166, v84, v85
	v_mov_b32_e32 v167, v166
	s_nop 1
	v_permlane32_swap_b32_e32 v166, v167
	v_max3_f32 v212, v211, v166, v167
	v_sub_f32_e32 v86, v86, v212
	v_exp_f32_e32 v167, v86
	v_sub_f32_e32 v86, v87, v212
	v_exp_f32_e32 v168, v86
	v_sub_f32_e32 v86, v88, v212
	v_exp_f32_e32 v169, v86
	v_sub_f32_e32 v86, v89, v212
	v_exp_f32_e32 v89, v86
	v_sub_f32_e32 v86, v90, v212
	v_exp_f32_e32 v90, v86
	v_sub_f32_e32 v86, v91, v212
	v_exp_f32_e32 v91, v86
	v_sub_f32_e32 v86, v92, v212
	v_exp_f32_e32 v92, v86
	v_sub_f32_e32 v86, v93, v212
	v_exp_f32_e32 v93, v86
	v_sub_f32_e32 v86, v94, v212
	v_exp_f32_e32 v94, v86
	v_sub_f32_e32 v86, v95, v212
	v_exp_f32_e32 v95, v86
	v_sub_f32_e32 v86, v96, v212
	v_exp_f32_e32 v96, v86
	v_sub_f32_e32 v86, v97, v212
	v_exp_f32_e32 v97, v86
	v_sub_f32_e32 v86, v98, v212
	v_exp_f32_e32 v98, v86
	v_sub_f32_e32 v86, v99, v212
	v_exp_f32_e32 v99, v86
	v_sub_f32_e32 v86, v100, v212
	v_sub_f32_e32 v166, v211, v212
	v_sub_f32_e32 v74, v74, v212
	v_exp_f32_e32 v100, v86
	v_sub_f32_e32 v86, v101, v212
	v_exp_f32_e32 v101, v86
	v_exp_f32_e32 v86, v166
	v_exp_f32_e32 v166, v74
	v_add_f32_e32 v74, 0, v167
	v_add_f32_e32 v74, v168, v74
	v_add_f32_e32 v74, v169, v74
	v_add_f32_e32 v74, v89, v74
	v_add_f32_e32 v74, v90, v74
	v_add_f32_e32 v74, v91, v74
	v_add_f32_e32 v74, v92, v74
	v_add_f32_e32 v74, v93, v74
	v_add_f32_e32 v74, v94, v74
	v_add_f32_e32 v74, v95, v74
	v_add_f32_e32 v74, v96, v74
	v_sub_f32_e32 v70, v70, v212
	v_add_f32_e32 v74, v97, v74
	v_sub_f32_e32 v71, v71, v212
	v_exp_f32_e32 v70, v70
	v_add_f32_e32 v74, v98, v74
	v_sub_f32_e32 v72, v72, v212
	v_exp_f32_e32 v71, v71
	v_add_f32_e32 v74, v99, v74
	v_sub_f32_e32 v73, v73, v212
	v_exp_f32_e32 v72, v72
	v_add_f32_e32 v74, v100, v74
	v_exp_f32_e32 v73, v73
	v_add_f32_e32 v74, v101, v74
	v_sub_f32_e32 v75, v75, v212
	v_add_f32_e32 v74, v70, v74
	v_sub_f32_e32 v76, v76, v212
	v_exp_f32_e32 v170, v75
	v_add_f32_e32 v74, v71, v74
	v_sub_f32_e32 v77, v77, v212
	v_exp_f32_e32 v171, v76
	v_add_f32_e32 v74, v72, v74
	v_sub_f32_e32 v78, v78, v212
	v_exp_f32_e32 v77, v77
	v_add_f32_e32 v74, v73, v74
	v_sub_f32_e32 v79, v79, v212
	v_exp_f32_e32 v172, v78
	v_add_f32_e32 v74, v166, v74
	v_sub_f32_e32 v80, v80, v212
	v_exp_f32_e32 v173, v79
	v_add_f32_e32 v74, v170, v74
	v_sub_f32_e32 v81, v81, v212
	v_exp_f32_e32 v174, v80
	v_add_f32_e32 v74, v171, v74
	v_sub_f32_e32 v82, v82, v212
	v_exp_f32_e32 v175, v81
	v_add_f32_e32 v74, v77, v74
	v_sub_f32_e32 v83, v83, v212
	v_exp_f32_e32 v176, v82
	v_add_f32_e32 v74, v172, v74
	v_sub_f32_e32 v84, v84, v212
	v_exp_f32_e32 v177, v83
	v_add_f32_e32 v74, v173, v74
	v_sub_f32_e32 v85, v85, v212
	v_exp_f32_e32 v178, v84
	v_add_f32_e32 v74, v174, v74
	v_exp_f32_e32 v179, v85
	v_add_f32_e32 v74, v175, v74
	v_add_f32_e32 v74, v176, v74
	v_add_f32_e32 v74, v177, v74
	v_add_f32_e32 v74, v178, v74
	v_add_f32_e32 v87, v179, v74
	v_mov_b32_e32 v88, v87
	s_nop 1
	v_permlane32_swap_b32_e32 v87, v88
	v_cmp_gt_f32_e32 vcc, 1.0, v86
	v_cvt_pk_bf16_f32 v82, v167, v168
	v_cvt_pk_bf16_f32 v83, v169, v89
	v_cvt_pk_bf16_f32 v84, v90, v91
	v_cvt_pk_bf16_f32 v85, v92, v93
	v_cvt_pk_bf16_f32 v78, v94, v95
	v_cvt_pk_bf16_f32 v79, v96, v97
	v_cvt_pk_bf16_f32 v80, v98, v99
	v_cvt_pk_bf16_f32 v81, v100, v101
	v_cvt_pk_bf16_f32 v74, v70, v71
	v_cvt_pk_bf16_f32 v75, v72, v73
	v_cvt_pk_bf16_f32 v76, v166, v170
	v_cvt_pk_bf16_f32 v77, v171, v77
	v_cvt_pk_bf16_f32 v70, v172, v173
	v_cvt_pk_bf16_f32 v71, v174, v175
	v_cvt_pk_bf16_f32 v72, v176, v177
	v_cvt_pk_bf16_f32 v73, v178, v179
	s_cbranch_vccz .LBB0_573
	s_and_saveexec_b64 s[22:23], s[38:39]
	ds_write_b32 v191, v86 offset:128
	s_or_b64 exec, exec, s[22:23]
	s_waitcnt lgkmcnt(0)
	v_lshl_add_u32 v89, v185, 2, s44
	ds_read_b128 v[90:93], v89 offset:224
	ds_read_b128 v[94:97], v89 offset:192
	ds_read_b128 v[98:101], v89 offset:160
	ds_read_b128 v[166:169], v89 offset:128
	s_waitcnt lgkmcnt(3)
	v_pk_mul_f32 v[34:35], v[34:35], v[92:93]
	s_waitcnt lgkmcnt(2)
	v_pk_mul_f32 v[30:31], v[30:31], v[96:97]
	s_waitcnt lgkmcnt(1)
	v_pk_mul_f32 v[26:27], v[26:27], v[100:101]
	s_waitcnt lgkmcnt(0)
	v_pk_mul_f32 v[22:23], v[22:23], v[168:169]
	v_pk_mul_f32 v[32:33], v[32:33], v[90:91]
	v_pk_mul_f32 v[28:29], v[28:29], v[94:95]
	v_pk_mul_f32 v[24:25], v[24:25], v[98:99]
	v_pk_mul_f32 v[20:21], v[20:21], v[166:167]
	v_pk_mul_f32 v[50:51], v[50:51], v[92:93]
	v_pk_mul_f32 v[46:47], v[46:47], v[96:97]
	v_pk_mul_f32 v[42:43], v[42:43], v[100:101]
	v_pk_mul_f32 v[38:39], v[38:39], v[168:169]
	v_pk_mul_f32 v[48:49], v[48:49], v[90:91]
	v_pk_mul_f32 v[44:45], v[44:45], v[94:95]
	v_pk_mul_f32 v[40:41], v[40:41], v[98:99]
	v_pk_mul_f32 v[36:37], v[36:37], v[166:167]
	v_pk_mul_f32 v[66:67], v[66:67], v[92:93]
	v_pk_mul_f32 v[62:63], v[62:63], v[96:97]
	v_pk_mul_f32 v[58:59], v[58:59], v[100:101]
	v_pk_mul_f32 v[54:55], v[54:55], v[168:169]
	v_pk_mul_f32 v[64:65], v[64:65], v[90:91]
	v_pk_mul_f32 v[60:61], v[60:61], v[94:95]
	v_pk_mul_f32 v[56:57], v[56:57], v[98:99]
	v_pk_mul_f32 v[52:53], v[52:53], v[166:167]
	v_pk_mul_f32 v[18:19], v[18:19], v[92:93]
	v_pk_mul_f32 v[14:15], v[14:15], v[96:97]
	v_pk_mul_f32 v[10:11], v[10:11], v[100:101]
	v_pk_mul_f32 v[6:7], v[6:7], v[168:169]
	v_pk_mul_f32 v[16:17], v[16:17], v[90:91]
	v_pk_mul_f32 v[12:13], v[12:13], v[94:95]
	v_pk_mul_f32 v[8:9], v[8:9], v[98:99]
	v_pk_mul_f32 v[4:5], v[4:5], v[166:167]

.LBB0_575:
	v_add_u32_e32 v70, 0x80, v210
	v_add_u32_e32 v72, 0xa0, v210
	s_movk_i32 s16, 0xff7f
	v_min_i32_e32 v70, s3, v70
	v_cmp_lt_i32_e32 vcc, s16, v210
	v_min_i32_e32 v72, s3, v72
	s_movk_i32 s3, 0xff5f
	v_cndmask_b32_e32 v70, 0, v70, vcc
	v_cmp_lt_i32_e32 vcc, s3, v210
	v_ashrrev_i32_e32 v71, 31, v70
	v_lshlrev_b64 v[70:71], s18, v[70:71]
	v_cndmask_b32_e32 v72, 0, v72, vcc
	v_ashrrev_i32_e32 v73, 31, v72
	v_lshlrev_b64 v[72:73], s18, v[72:73]
	v_lshl_add_u64 v[70:71], v[70:71], 0, v[2:3]
	v_lshl_add_u64 v[72:73], v[72:73], 0, v[2:3]
	v_lshlrev_b64 v[70:71], 1, v[70:71]
	v_lshlrev_b64 v[72:73], 1, v[72:73]
	v_lshl_add_u64 v[74:75], s[12:13], 0, v[70:71]
	v_lshl_add_u64 v[76:77], s[12:13], 0, v[72:73]
	v_lshl_add_u64 v[72:73], s[10:11], 0, v[72:73]
	s_waitcnt vmcnt(4)
	s_waitcnt vmcnt(7)
	ds_write_b128 v196, v[142:145] offset:16384
	s_waitcnt vmcnt(6)
	ds_write_b128 v197, v[146:149] offset:16384
	s_waitcnt vmcnt(4)
	ds_write_b128 v198, v[162:165] offset:49152
	ds_write_b128 v199, v[158:161] offset:49152
	s_waitcnt lgkmcnt(0)
	s_barrier
	global_load_dwordx4 v[142:145], v[74:75], off
	global_load_dwordx4 v[146:149], v[76:77], off
	v_lshl_add_u64 v[70:71], s[10:11], 0, v[70:71]
	global_load_dwordx4 v[166:169], v[72:73], off
	global_load_dwordx4 v[170:173], v[70:71], off
	s_cmp_gt_u32 s19, 2
	s_cbranch_scc1 .LBB0_581
	ds_read_b128 v[70:73], v207 offset:49152
	ds_read_b128 v[74:77], v207 offset:57344
	ds_read_b128 v[158:161], v206 offset:49152
	ds_read_b128 v[162:165], v206 offset:57344
	s_waitcnt lgkmcnt(3)
	v_mfma_f32_32x32x16_bf16 v[86:101], v[70:73], v[110:113], 0
	s_waitcnt lgkmcnt(2)
	v_mfma_f32_32x32x16_bf16 v[70:85], v[74:77], v[110:113], 0
	ds_read_b128 v[214:217], v205 offset:49152
	ds_read_b128 v[218:221], v205 offset:57344
	s_waitcnt lgkmcnt(3)
	v_mfma_f32_32x32x16_bf16 v[86:101], v[158:161], v[130:133], v[86:101]
	s_waitcnt lgkmcnt(2)
	v_mfma_f32_32x32x16_bf16 v[70:85], v[162:165], v[130:133], v[70:85]
	ds_read_b128 v[158:161], v204 offset:49152
	ds_read_b128 v[162:165], v204 offset:57344
	s_waitcnt lgkmcnt(3)
	v_mfma_f32_32x32x16_bf16 v[86:101], v[214:217], v[126:129], v[86:101]
	s_waitcnt lgkmcnt(2)
	v_mfma_f32_32x32x16_bf16 v[70:85], v[218:221], v[126:129], v[70:85]
	ds_read_b128 v[214:217], v203 offset:49152
	ds_read_b128 v[218:221], v203 offset:57344
	s_waitcnt lgkmcnt(3)
	v_mfma_f32_32x32x16_bf16 v[86:101], v[158:161], v[122:125], v[86:101]
	s_waitcnt lgkmcnt(2)
	v_mfma_f32_32x32x16_bf16 v[70:85], v[162:165], v[122:125], v[70:85]
	ds_read_b128 v[158:161], v202 offset:49152
	ds_read_b128 v[162:165], v202 offset:57344
	s_waitcnt lgkmcnt(3)
	v_mfma_f32_32x32x16_bf16 v[86:101], v[214:217], v[118:121], v[86:101]
	s_waitcnt lgkmcnt(2)
	v_mfma_f32_32x32x16_bf16 v[70:85], v[218:221], v[118:121], v[70:85]
	ds_read_b128 v[214:217], v201 offset:49152
	ds_read_b128 v[218:221], v201 offset:57344
	s_waitcnt lgkmcnt(3)
	v_mfma_f32_32x32x16_bf16 v[86:101], v[158:161], v[114:117], v[86:101]
	s_waitcnt lgkmcnt(2)
	v_mfma_f32_32x32x16_bf16 v[70:85], v[162:165], v[114:117], v[70:85]
	ds_read_b128 v[158:161], v200 offset:49152
	ds_read_b128 v[162:165], v200 offset:57344
	s_waitcnt lgkmcnt(3)
	v_mfma_f32_32x32x16_bf16 v[86:101], v[214:217], v[106:109], v[86:101]
	s_waitcnt lgkmcnt(2)
	v_mfma_f32_32x32x16_bf16 v[70:85], v[218:221], v[106:109], v[70:85]
	s_waitcnt lgkmcnt(1)
	v_mfma_f32_32x32x16_bf16 v[86:101], v[158:161], v[102:105], v[86:101]
	s_waitcnt lgkmcnt(0)
	v_mfma_f32_32x32x16_bf16 v[70:85], v[162:165], v[102:105], v[70:85]
	v_add_u32_e32 v158, 0xc0, v194
	v_sub_u32_e32 v159, v192, v158
	v_cvt_f32_i32_e32 v159, v159
	v_readfirstlane_b32 s40, v158
	s_add_i32 s41, s40, 64
	s_cmp_lt_i32 s40, 0
	s_cbranch_scc1 .Lam_out_3
	s_cmp_gt_i32 s41, s45
	s_cbranch_scc1 .Lam_out_3
	v_mov_b32_e32 v158, v159
	v_add_f32_e32 v160, 0xc2000000, v159
	v_cmp_le_f32_e64 vcc, |v158|, s76
	v_cmp_le_f32_e64 s[10:11], |v160|, s76
	v_mul_f32_e64 v158, v193, |v158|
	v_mul_f32_e64 v160, v193, |v160|
	v_fmac_f32_e32 v158, 0x3e0293ee, v86
	v_fmac_f32_e32 v160, 0x3e0293ee, v70
	v_cndmask_b32_e32 v86, v234, v158, vcc
	v_cndmask_b32_e64 v70, v234, v160, s[10:11]
	v_add_f32_e32 v158, -1.0, v159
	v_add_f32_e32 v160, 0xc2040000, v159
	v_cmp_le_f32_e64 vcc, |v158|, s76
	v_cmp_le_f32_e64 s[10:11], |v160|, s76
	v_mul_f32_e64 v158, v193, |v158|
	v_mul_f32_e64 v160, v193, |v160|
	v_fmac_f32_e32 v158, 0x3e0293ee, v87
	v_fmac_f32_e32 v160, 0x3e0293ee, v71
	v_cndmask_b32_e32 v87, v234, v158, vcc
	v_cndmask_b32_e64 v71, v234, v160, s[10:11]
	v_add_f32_e32 v158, -2.0, v159
	v_add_f32_e32 v160, 0xc2080000, v159
	v_cmp_le_f32_e64 vcc, |v158|, s76
	v_cmp_le_f32_e64 s[10:11], |v160|, s76
	v_mul_f32_e64 v158, v193, |v158|
	v_mul_f32_e64 v160, v193, |v160|
	v_fmac_f32_e32 v158, 0x3e0293ee, v88
	v_fmac_f32_e32 v160, 0x3e0293ee, v72
	v_cndmask_b32_e32 v88, v234, v158, vcc
	v_cndmask_b32_e64 v72, v234, v160, s[10:11]
	v_add_f32_e32 v158, 0xc0400000, v159
	v_add_f32_e32 v160, 0xc20c0000, v159
	v_cmp_le_f32_e64 vcc, |v158|, s76
	v_cmp_le_f32_e64 s[10:11], |v160|, s76
	v_mul_f32_e64 v158, v193, |v158|
	v_mul_f32_e64 v160, v193, |v160|
	v_fmac_f32_e32 v158, 0x3e0293ee, v89
	v_fmac_f32_e32 v160, 0x3e0293ee, v73
	v_cndmask_b32_e32 v89, v234, v158, vcc
	v_cndmask_b32_e64 v73, v234, v160, s[10:11]
	v_add_f32_e32 v158, 0xc1000000, v159
	v_add_f32_e32 v160, 0xc2200000, v159
	v_cmp_le_f32_e64 vcc, |v158|, s76
	v_cmp_le_f32_e64 s[10:11], |v160|, s76
	v_mul_f32_e64 v158, v193, |v158|
	v_mul_f32_e64 v160, v193, |v160|
	v_fmac_f32_e32 v158, 0x3e0293ee, v90
	v_fmac_f32_e32 v160, 0x3e0293ee, v74
	v_cndmask_b32_e32 v90, v234, v158, vcc
	v_cndmask_b32_e64 v74, v234, v160, s[10:11]
	v_add_f32_e32 v158, 0xc1100000, v159
	v_add_f32_e32 v160, 0xc2240000, v159
	v_cmp_le_f32_e64 vcc, |v158|, s76
	v_cmp_le_f32_e64 s[10:11], |v160|, s76
	v_mul_f32_e64 v158, v193, |v158|
	v_mul_f32_e64 v160, v193, |v160|
	v_fmac_f32_e32 v158, 0x3e0293ee, v91
	v_fmac_f32_e32 v160, 0x3e0293ee, v75
	v_cndmask_b32_e32 v91, v234, v158, vcc
	v_cndmask_b32_e64 v75, v234, v160, s[10:11]
	v_add_f32_e32 v158, 0xc1200000, v159
	v_add_f32_e32 v160, 0xc2280000, v159
	v_cmp_le_f32_e64 vcc, |v158|, s76
	v_cmp_le_f32_e64 s[10:11], |v160|, s76
	v_mul_f32_e64 v158, v193, |v158|
	v_mul_f32_e64 v160, v193, |v160|
	v_fmac_f32_e32 v158, 0x3e0293ee, v92
	v_fmac_f32_e32 v160, 0x3e0293ee, v76
	v_cndmask_b32_e32 v92, v234, v158, vcc
	v_cndmask_b32_e64 v76, v234, v160, s[10:11]
	v_add_f32_e32 v158, 0xc1300000, v159
	v_add_f32_e32 v160, 0xc22c0000, v159
	v_cmp_le_f32_e64 vcc, |v158|, s76
	v_cmp_le_f32_e64 s[10:11], |v160|, s76
	v_mul_f32_e64 v158, v193, |v158|
	v_mul_f32_e64 v160, v193, |v160|
	v_fmac_f32_e32 v158, 0x3e0293ee, v93
	v_fmac_f32_e32 v160, 0x3e0293ee, v77
	v_cndmask_b32_e32 v93, v234, v158, vcc
	v_cndmask_b32_e64 v77, v234, v160, s[10:11]
	v_add_f32_e32 v158, 0xc1800000, v159
	v_add_f32_e32 v160, 0xc2400000, v159
	v_cmp_le_f32_e64 vcc, |v158|, s76
	v_cmp_le_f32_e64 s[10:11], |v160|, s76
	v_mul_f32_e64 v158, v193, |v158|
	v_mul_f32_e64 v160, v193, |v160|
	v_fmac_f32_e32 v158, 0x3e0293ee, v94
	v_fmac_f32_e32 v160, 0x3e0293ee, v78
	v_cndmask_b32_e32 v94, v234, v158, vcc
	v_cndmask_b32_e64 v78, v234, v160, s[10:11]
	v_add_f32_e32 v158, 0xc1880000, v159
	v_add_f32_e32 v160, 0xc2440000, v159
	v_cmp_le_f32_e64 vcc, |v158|, s76
	v_cmp_le_f32_e64 s[10:11], |v160|, s76
	v_mul_f32_e64 v158, v193, |v158|
	v_mul_f32_e64 v160, v193, |v160|
	v_fmac_f32_e32 v158, 0x3e0293ee, v95
	v_fmac_f32_e32 v160, 0x3e0293ee, v79
	v_cndmask_b32_e32 v95, v234, v158, vcc
	v_cndmask_b32_e64 v79, v234, v160, s[10:11]
	v_add_f32_e32 v158, 0xc1900000, v159
	v_add_f32_e32 v160, 0xc2480000, v159
	v_cmp_le_f32_e64 vcc, |v158|, s76
	v_cmp_le_f32_e64 s[10:11], |v160|, s76
	v_mul_f32_e64 v158, v193, |v158|
	v_mul_f32_e64 v160, v193, |v160|
	v_fmac_f32_e32 v158, 0x3e0293ee, v96
	v_fmac_f32_e32 v160, 0x3e0293ee, v80
	v_cndmask_b32_e32 v96, v234, v158, vcc
	v_cndmask_b32_e64 v80, v234, v160, s[10:11]
	v_add_f32_e32 v158, 0xc1980000, v159
	v_add_f32_e32 v160, 0xc24c0000, v159
	v_cmp_le_f32_e64 vcc, |v158|, s76
	v_cmp_le_f32_e64 s[10:11], |v160|, s76
	v_mul_f32_e64 v158, v193, |v158|
	v_mul_f32_e64 v160, v193, |v160|
	v_fmac_f32_e32 v158, 0x3e0293ee, v97
	v_fmac_f32_e32 v160, 0x3e0293ee, v81
	v_cndmask_b32_e32 v97, v234, v158, vcc
	v_cndmask_b32_e64 v81, v234, v160, s[10:11]
	v_add_f32_e32 v158, 0xc1c00000, v159
	v_add_f32_e32 v160, 0xc2600000, v159
	v_cmp_le_f32_e64 vcc, |v158|, s76
	v_cmp_le_f32_e64 s[10:11], |v160|, s76
	v_mul_f32_e64 v158, v193, |v158|
	v_mul_f32_e64 v160, v193, |v160|
	v_fmac_f32_e32 v158, 0x3e0293ee, v98
	v_fmac_f32_e32 v160, 0x3e0293ee, v82
	v_cndmask_b32_e32 v98, v234, v158, vcc
	v_cndmask_b32_e64 v82, v234, v160, s[10:11]
	v_add_f32_e32 v158, 0xc1c80000, v159
	v_add_f32_e32 v160, 0xc2640000, v159
	v_cmp_le_f32_e64 vcc, |v158|, s76
	v_cmp_le_f32_e64 s[10:11], |v160|, s76
	v_mul_f32_e64 v158, v193, |v158|
	v_mul_f32_e64 v160, v193, |v160|
	v_fmac_f32_e32 v158, 0x3e0293ee, v99
	v_fmac_f32_e32 v160, 0x3e0293ee, v83
	v_cndmask_b32_e32 v99, v234, v158, vcc
	v_cndmask_b32_e64 v83, v234, v160, s[10:11]
	v_add_f32_e32 v158, 0xc1d00000, v159
	v_add_f32_e32 v160, 0xc2680000, v159
	v_cmp_le_f32_e64 vcc, |v158|, s76
	v_cmp_le_f32_e64 s[10:11], |v160|, s76
	v_mul_f32_e64 v158, v193, |v158|
	v_mul_f32_e64 v160, v193, |v160|
	v_fmac_f32_e32 v158, 0x3e0293ee, v100
	v_fmac_f32_e32 v160, 0x3e0293ee, v84
	v_cndmask_b32_e32 v100, v234, v158, vcc
	v_cndmask_b32_e64 v84, v234, v160, s[10:11]
	v_add_f32_e32 v158, 0xc1d80000, v159
	v_add_f32_e32 v160, 0xc26c0000, v159
	v_cmp_le_f32_e64 vcc, |v158|, s76
	v_cmp_le_f32_e64 s[10:11], |v160|, s76
	v_mul_f32_e64 v158, v193, |v158|
	v_mul_f32_e64 v160, v193, |v160|
	v_fmac_f32_e32 v158, 0x3e0293ee, v101
	v_fmac_f32_e32 v160, 0x3e0293ee, v85
	v_cndmask_b32_e32 v101, v234, v158, vcc
	v_cndmask_b32_e64 v85, v234, v160, s[10:11]
	s_branch .Lam_done_3

.Lam_done_3:
	v_max_f32_e32 v158, v86, v87
	v_max3_f32 v158, v158, v88, v89
	v_max3_f32 v158, v158, v90, v91
	v_max3_f32 v158, v158, v92, v93
	v_max3_f32 v158, v158, v94, v95
	v_max3_f32 v158, v158, v96, v97
	v_max3_f32 v158, v158, v98, v99
	v_max3_f32 v158, v158, v100, v101
	v_max3_f32 v158, v158, v70, v71
	v_max3_f32 v158, v158, v72, v73
	v_max3_f32 v158, v158, v74, v75
	v_max3_f32 v158, v158, v76, v77
	v_max3_f32 v158, v158, v78, v79
	v_max3_f32 v158, v158, v80, v81
	v_max3_f32 v158, v158, v82, v83
	v_max3_f32 v158, v158, v84, v85
	v_mov_b32_e32 v159, v158
	s_nop 1
	v_permlane32_swap_b32_e32 v158, v159
	v_max3_f32 v209, v212, v158, v159
	v_sub_f32_e32 v86, v86, v209
	v_exp_f32_e32 v159, v86
	v_sub_f32_e32 v86, v87, v209
	v_exp_f32_e32 v160, v86
	v_sub_f32_e32 v86, v88, v209
	v_exp_f32_e32 v161, v86
	v_sub_f32_e32 v86, v89, v209
	v_exp_f32_e32 v89, v86
	v_sub_f32_e32 v86, v90, v209
	v_exp_f32_e32 v90, v86
	v_sub_f32_e32 v86, v91, v209
	v_exp_f32_e32 v91, v86
	v_sub_f32_e32 v86, v92, v209
	v_exp_f32_e32 v92, v86
	v_sub_f32_e32 v86, v93, v209
	v_exp_f32_e32 v93, v86
	v_sub_f32_e32 v86, v94, v209
	v_exp_f32_e32 v94, v86
	v_sub_f32_e32 v86, v95, v209
	v_exp_f32_e32 v95, v86
	v_sub_f32_e32 v86, v96, v209
	v_exp_f32_e32 v96, v86
	v_sub_f32_e32 v86, v97, v209
	v_exp_f32_e32 v97, v86
	v_sub_f32_e32 v86, v98, v209
	v_exp_f32_e32 v98, v86
	v_sub_f32_e32 v86, v99, v209
	v_exp_f32_e32 v99, v86
	v_sub_f32_e32 v86, v100, v209
	v_sub_f32_e32 v158, v212, v209
	v_sub_f32_e32 v74, v74, v209
	v_exp_f32_e32 v100, v86
	v_sub_f32_e32 v86, v101, v209
	v_exp_f32_e32 v101, v86
	v_exp_f32_e32 v86, v158
	v_exp_f32_e32 v158, v74
	v_add_f32_e32 v74, 0, v159
	v_add_f32_e32 v74, v160, v74
	v_add_f32_e32 v74, v161, v74
	v_add_f32_e32 v74, v89, v74
	v_add_f32_e32 v74, v90, v74
	v_add_f32_e32 v74, v91, v74
	v_add_f32_e32 v74, v92, v74
	v_add_f32_e32 v74, v93, v74
	v_add_f32_e32 v74, v94, v74
	v_add_f32_e32 v74, v95, v74
	v_add_f32_e32 v74, v96, v74
	v_sub_f32_e32 v70, v70, v209
	v_add_f32_e32 v74, v97, v74
	v_sub_f32_e32 v71, v71, v209
	v_exp_f32_e32 v70, v70
	v_add_f32_e32 v74, v98, v74
	v_sub_f32_e32 v72, v72, v209
	v_exp_f32_e32 v71, v71
	v_add_f32_e32 v74, v99, v74
	v_sub_f32_e32 v73, v73, v209
	v_exp_f32_e32 v72, v72
	v_add_f32_e32 v74, v100, v74
	v_exp_f32_e32 v73, v73
	v_add_f32_e32 v74, v101, v74
	v_sub_f32_e32 v75, v75, v209
	v_add_f32_e32 v74, v70, v74
	v_sub_f32_e32 v76, v76, v209
	v_exp_f32_e32 v162, v75
	v_add_f32_e32 v74, v71, v74
	v_sub_f32_e32 v77, v77, v209
	v_exp_f32_e32 v163, v76
	v_add_f32_e32 v74, v72, v74
	v_sub_f32_e32 v78, v78, v209
	v_exp_f32_e32 v77, v77
	v_add_f32_e32 v74, v73, v74
	v_sub_f32_e32 v79, v79, v209
	v_exp_f32_e32 v164, v78
	v_add_f32_e32 v74, v158, v74
	v_sub_f32_e32 v80, v80, v209
	v_exp_f32_e32 v165, v79
	v_add_f32_e32 v74, v162, v74
	v_sub_f32_e32 v81, v81, v209
	v_exp_f32_e32 v174, v80
	v_add_f32_e32 v74, v163, v74
	v_sub_f32_e32 v82, v82, v209
	v_exp_f32_e32 v175, v81
	v_add_f32_e32 v74, v77, v74
	v_sub_f32_e32 v83, v83, v209
	v_exp_f32_e32 v176, v82
	v_add_f32_e32 v74, v164, v74
	v_sub_f32_e32 v84, v84, v209
	v_exp_f32_e32 v177, v83
	v_add_f32_e32 v74, v165, v74
	v_sub_f32_e32 v85, v85, v209
	v_exp_f32_e32 v178, v84
	v_add_f32_e32 v74, v174, v74
	v_exp_f32_e32 v179, v85
	v_add_f32_e32 v74, v175, v74
	v_add_f32_e32 v74, v176, v74
	v_add_f32_e32 v74, v177, v74
	v_add_f32_e32 v74, v178, v74
	v_add_f32_e32 v87, v179, v74
	v_mov_b32_e32 v88, v87
	s_nop 1
	v_permlane32_swap_b32_e32 v87, v88
	v_cmp_gt_f32_e32 vcc, 1.0, v86
	v_cvt_pk_bf16_f32 v82, v159, v160
	v_cvt_pk_bf16_f32 v83, v161, v89
	v_cvt_pk_bf16_f32 v84, v90, v91
	v_cvt_pk_bf16_f32 v85, v92, v93
	v_cvt_pk_bf16_f32 v78, v94, v95
	v_cvt_pk_bf16_f32 v79, v96, v97
	v_cvt_pk_bf16_f32 v80, v98, v99
	v_cvt_pk_bf16_f32 v81, v100, v101
	v_cvt_pk_bf16_f32 v74, v70, v71
	v_cvt_pk_bf16_f32 v75, v72, v73
	v_cvt_pk_bf16_f32 v76, v158, v162
	v_cvt_pk_bf16_f32 v77, v163, v77
	v_cvt_pk_bf16_f32 v70, v164, v165
	v_cvt_pk_bf16_f32 v71, v174, v175
	v_cvt_pk_bf16_f32 v72, v176, v177
	v_cvt_pk_bf16_f32 v73, v178, v179
	s_cbranch_vccz .LBB0_580
	s_and_saveexec_b64 s[10:11], s[38:39]
	ds_write_b32 v191, v86 offset:128
	s_or_b64 exec, exec, s[10:11]
	s_waitcnt lgkmcnt(0)
	v_lshl_add_u32 v89, v185, 2, s44
	ds_read_b128 v[90:93], v89 offset:224
	ds_read_b128 v[94:97], v89 offset:192
	ds_read_b128 v[98:101], v89 offset:160
	ds_read_b128 v[158:161], v89 offset:128
	s_waitcnt lgkmcnt(3)
	v_pk_mul_f32 v[34:35], v[34:35], v[92:93]
	s_waitcnt lgkmcnt(2)
	v_pk_mul_f32 v[30:31], v[30:31], v[96:97]
	s_waitcnt lgkmcnt(1)
	v_pk_mul_f32 v[26:27], v[26:27], v[100:101]
	s_waitcnt lgkmcnt(0)
	v_pk_mul_f32 v[22:23], v[22:23], v[160:161]
	v_pk_mul_f32 v[32:33], v[32:33], v[90:91]
	v_pk_mul_f32 v[28:29], v[28:29], v[94:95]
	v_pk_mul_f32 v[24:25], v[24:25], v[98:99]
	v_pk_mul_f32 v[20:21], v[20:21], v[158:159]
	v_pk_mul_f32 v[50:51], v[50:51], v[92:93]
	v_pk_mul_f32 v[46:47], v[46:47], v[96:97]
	v_pk_mul_f32 v[42:43], v[42:43], v[100:101]
	v_pk_mul_f32 v[38:39], v[38:39], v[160:161]
	v_pk_mul_f32 v[48:49], v[48:49], v[90:91]
	v_pk_mul_f32 v[44:45], v[44:45], v[94:95]
	v_pk_mul_f32 v[40:41], v[40:41], v[98:99]
	v_pk_mul_f32 v[36:37], v[36:37], v[158:159]
	v_pk_mul_f32 v[66:67], v[66:67], v[92:93]
	v_pk_mul_f32 v[62:63], v[62:63], v[96:97]
	v_pk_mul_f32 v[58:59], v[58:59], v[100:101]
	v_pk_mul_f32 v[54:55], v[54:55], v[160:161]
	v_pk_mul_f32 v[64:65], v[64:65], v[90:91]
	v_pk_mul_f32 v[60:61], v[60:61], v[94:95]
	v_pk_mul_f32 v[56:57], v[56:57], v[98:99]
	v_pk_mul_f32 v[52:53], v[52:53], v[158:159]
	v_pk_mul_f32 v[18:19], v[18:19], v[92:93]
	v_pk_mul_f32 v[14:15], v[14:15], v[96:97]
	v_pk_mul_f32 v[10:11], v[10:11], v[100:101]
	v_pk_mul_f32 v[6:7], v[6:7], v[160:161]
	v_pk_mul_f32 v[16:17], v[16:17], v[90:91]
	v_pk_mul_f32 v[12:13], v[12:13], v[94:95]
	v_pk_mul_f32 v[8:9], v[8:9], v[98:99]
	v_pk_mul_f32 v[4:5], v[4:5], v[158:159]

.LBB0_582:
	v_readlane_b32 s3, v251, 2
	s_add_i32 s3, s3, s26
	s_cmpk_gt_i32 s3, 0x8ff
	s_cselect_b64 s[10:11], -1, 0
	s_cmpk_lt_i32 s3, 0x900
	s_cselect_b32 s12, s3, s26
	s_ashr_i32 s13, s12, 3
	s_andn2_b32 s13, s13, 31
	s_and_b32 s16, s12, 31
	s_or_b32 s13, s13, s16
	s_mul_hi_i32 s16, s13, 0x2aaaaaab
	s_lshr_b32 s17, s16, 31
	s_ashr_i32 s16, s16, 4
	s_add_i32 s16, s16, s17
	s_mul_i32 s17, s16, 0x60
	s_sub_i32 s13, s13, s17
	s_lshl_b32 s17, s13, 8
	s_add_i32 s17, s17, 0x7fffe000
	s_and_b32 s17, s17, 0x7ffff000
	s_addk_i32 s17, 0x2000
	s_and_b32 s18, s13, 15
	s_cmp_lt_i32 s13, 32
	s_movk_i32 s19, 0x1000
	s_cselect_b32 s17, 0, s17
	s_cselect_b32 s19, 0x2000, s19
	s_cselect_b32 s13, s13, s18
	s_lshl_b32 s16, s16, 1
	s_lshl_b32 s18, 1, s16
	v_cvt_f32_u32_e32 v70, s18
	s_sub_i32 s26, 0, s18
	s_ashr_i32 s22, s13, 31
	s_add_i32 s23, s13, s22
	v_rcp_iflag_f32_e32 v70, v70
	s_xor_b32 s23, s23, s22
	s_bfe_u32 s12, s12, 0x30005
	s_mul_i32 s12, s12, 0x600000
	v_mul_f32_e32 v70, 0x4f7ffffe, v70
	v_cvt_u32_f32_e32 v70, v70
	s_waitcnt vmcnt(4)
	s_waitcnt vmcnt(7)
	ds_write_b128 v196, v[134:137]
	s_waitcnt vmcnt(6)
	ds_write_b128 v197, v[138:141]
	s_waitcnt vmcnt(4)
	ds_write_b128 v198, v[154:157] offset:32768
	ds_write_b128 v199, v[150:153] offset:32768
	s_waitcnt lgkmcnt(0)
	v_readfirstlane_b32 s27, v70
	s_mul_i32 s26, s26, s27
	s_mul_hi_u32 s26, s27, s26
	s_add_i32 s27, s27, s26
	s_mul_hi_u32 s26, s23, s27
	s_mul_i32 s27, s26, s18
	s_sub_i32 s23, s23, s27
	s_sub_i32 s27, s23, s18
	s_add_i32 s40, s26, 1
	s_cmp_ge_u32 s23, s18
	s_cselect_b32 s26, s40, s26
	s_cselect_b32 s23, s27, s23
	s_add_i32 s27, s26, 1
	s_cmp_ge_u32 s23, s18
	s_cselect_b32 s23, s27, s26
	s_xor_b32 s23, s23, s22
	s_sub_i32 s22, s23, s22
	s_mul_i32 s18, s22, s18
	s_sub_i32 s13, s13, s18
	s_lshl_b32 s47, s22, 8
	s_lshr_b32 s51, s19, s16
	s_add_u32 s48, s70, s12
	s_addc_u32 s49, s71, 0
	s_add_i32 s22, s13, s17
	s_ashr_i32 s23, s22, 31
	s_lshl_b64 s[12:13], s[22:23], 8
	s_add_u32 s17, s48, s12
	s_addc_u32 s19, s49, s13
	s_add_u32 s12, s17, 0x3000000
	s_addc_u32 s13, s19, 0
	s_add_u32 s18, s17, 0x6000000
	s_addc_u32 s19, s19, 0
	s_sub_i32 s17, s47, 64
	v_add_u32_e32 v72, s17, v195
	s_add_i32 s51, s51, -1
	v_add_u32_e32 v73, 32, v72
	v_min_i32_e32 v70, s51, v72
	v_cmp_lt_i32_e32 vcc, -1, v72
	s_movk_i32 s17, 0xffdf
	v_min_i32_e32 v73, s51, v73
	v_cndmask_b32_e32 v70, 0, v70, vcc
	v_cmp_lt_i32_e32 vcc, s17, v72
	v_ashrrev_i32_e32 v71, 31, v70
	s_add_u32 s50, s16, 7
	v_cndmask_b32_e32 v72, 0, v73, vcc
	v_ashrrev_i32_e32 v73, 31, v72
	v_lshlrev_b64 v[70:71], s50, v[70:71]
	v_lshl_add_u64 v[70:71], v[2:3], 0, v[70:71]
	v_lshlrev_b64 v[72:73], s50, v[72:73]
	v_lshlrev_b64 v[70:71], 1, v[70:71]
	v_lshl_add_u64 v[72:73], v[2:3], 0, v[72:73]
	v_lshl_add_u64 v[74:75], s[18:19], 0, v[70:71]
	v_lshlrev_b64 v[72:73], 1, v[72:73]
	v_lshl_add_u64 v[76:77], s[18:19], 0, v[72:73]
	v_lshl_add_u64 v[70:71], s[12:13], 0, v[70:71]
	v_lshl_add_u64 v[72:73], s[12:13], 0, v[72:73]
	s_barrier
	global_load_dwordx4 v[162:165], v[74:75], off
	global_load_dwordx4 v[158:161], v[76:77], off
	global_load_dwordx4 v[154:157], v[70:71], off
	global_load_dwordx4 v[150:153], v[72:73], off
	s_add_i32 s16, s46, -5
	s_cmp_lt_u32 s16, -3
	s_cbranch_scc1 .LBB0_588
	ds_read_b128 v[70:73], v207 offset:32768
	ds_read_b128 v[74:77], v207 offset:40960
	ds_read_b128 v[134:137], v206 offset:32768
	ds_read_b128 v[138:141], v206 offset:40960
	s_waitcnt lgkmcnt(3)
	v_mfma_f32_32x32x16_bf16 v[86:101], v[70:73], v[110:113], 0
	s_waitcnt lgkmcnt(2)
	v_mfma_f32_32x32x16_bf16 v[70:85], v[74:77], v[110:113], 0
	ds_read_b128 v[210:213], v205 offset:32768
	ds_read_b128 v[214:217], v205 offset:40960
	s_waitcnt lgkmcnt(3)
	v_mfma_f32_32x32x16_bf16 v[86:101], v[134:137], v[130:133], v[86:101]
	s_waitcnt lgkmcnt(2)
	v_mfma_f32_32x32x16_bf16 v[70:85], v[138:141], v[130:133], v[70:85]
	ds_read_b128 v[134:137], v204 offset:32768
	ds_read_b128 v[138:141], v204 offset:40960
	s_waitcnt lgkmcnt(3)
	v_mfma_f32_32x32x16_bf16 v[86:101], v[210:213], v[126:129], v[86:101]
	s_waitcnt lgkmcnt(2)
	v_mfma_f32_32x32x16_bf16 v[70:85], v[214:217], v[126:129], v[70:85]
	ds_read_b128 v[210:213], v203 offset:32768
	ds_read_b128 v[214:217], v203 offset:40960
	s_waitcnt lgkmcnt(3)
	v_mfma_f32_32x32x16_bf16 v[86:101], v[134:137], v[122:125], v[86:101]
	s_waitcnt lgkmcnt(2)
	v_mfma_f32_32x32x16_bf16 v[70:85], v[138:141], v[122:125], v[70:85]
	ds_read_b128 v[134:137], v202 offset:32768
	ds_read_b128 v[138:141], v202 offset:40960
	s_waitcnt lgkmcnt(3)
	v_mfma_f32_32x32x16_bf16 v[86:101], v[210:213], v[118:121], v[86:101]
	s_waitcnt lgkmcnt(2)
	v_mfma_f32_32x32x16_bf16 v[70:85], v[214:217], v[118:121], v[70:85]
	ds_read_b128 v[210:213], v201 offset:32768
	ds_read_b128 v[214:217], v201 offset:40960
	s_waitcnt lgkmcnt(3)
	v_mfma_f32_32x32x16_bf16 v[86:101], v[134:137], v[114:117], v[86:101]
	s_waitcnt lgkmcnt(2)
	v_mfma_f32_32x32x16_bf16 v[70:85], v[138:141], v[114:117], v[70:85]
	ds_read_b128 v[134:137], v200 offset:32768
	ds_read_b128 v[138:141], v200 offset:40960
	s_waitcnt lgkmcnt(3)
	v_mfma_f32_32x32x16_bf16 v[86:101], v[210:213], v[106:109], v[86:101]
	s_waitcnt lgkmcnt(2)
	v_mfma_f32_32x32x16_bf16 v[70:85], v[214:217], v[106:109], v[70:85]
	s_waitcnt lgkmcnt(1)
	v_mfma_f32_32x32x16_bf16 v[86:101], v[134:137], v[102:105], v[86:101]
	s_waitcnt lgkmcnt(0)
	v_mfma_f32_32x32x16_bf16 v[70:85], v[138:141], v[102:105], v[70:85]
	v_add_u32_e32 v134, 0x100, v194
	v_sub_u32_e32 v135, v192, v134
	v_cvt_f32_i32_e32 v135, v135
	v_readfirstlane_b32 s40, v134
	s_add_i32 s41, s40, 64
	s_cmp_lt_i32 s40, 0
	s_cbranch_scc1 .Lam_out_4
	s_cmp_gt_i32 s41, s45
	s_cbranch_scc1 .Lam_out_4
	v_mov_b32_e32 v134, v135
	v_add_f32_e32 v136, 0xc2000000, v135
	v_cmp_le_f32_e64 vcc, |v134|, s76
	v_cmp_le_f32_e64 s[16:17], |v136|, s76
	v_mul_f32_e64 v134, v193, |v134|
	v_mul_f32_e64 v136, v193, |v136|
	v_fmac_f32_e32 v134, 0x3e0293ee, v86
	v_fmac_f32_e32 v136, 0x3e0293ee, v70
	v_cndmask_b32_e32 v86, v234, v134, vcc
	v_cndmask_b32_e64 v70, v234, v136, s[16:17]
	v_add_f32_e32 v134, -1.0, v135
	v_add_f32_e32 v136, 0xc2040000, v135
	v_cmp_le_f32_e64 vcc, |v134|, s76
	v_cmp_le_f32_e64 s[16:17], |v136|, s76
	v_mul_f32_e64 v134, v193, |v134|
	v_mul_f32_e64 v136, v193, |v136|
	v_fmac_f32_e32 v134, 0x3e0293ee, v87
	v_fmac_f32_e32 v136, 0x3e0293ee, v71
	v_cndmask_b32_e32 v87, v234, v134, vcc
	v_cndmask_b32_e64 v71, v234, v136, s[16:17]
	v_add_f32_e32 v134, -2.0, v135
	v_add_f32_e32 v136, 0xc2080000, v135
	v_cmp_le_f32_e64 vcc, |v134|, s76
	v_cmp_le_f32_e64 s[16:17], |v136|, s76
	v_mul_f32_e64 v134, v193, |v134|
	v_mul_f32_e64 v136, v193, |v136|
	v_fmac_f32_e32 v134, 0x3e0293ee, v88
	v_fmac_f32_e32 v136, 0x3e0293ee, v72
	v_cndmask_b32_e32 v88, v234, v134, vcc
	v_cndmask_b32_e64 v72, v234, v136, s[16:17]
	v_add_f32_e32 v134, 0xc0400000, v135
	v_add_f32_e32 v136, 0xc20c0000, v135
	v_cmp_le_f32_e64 vcc, |v134|, s76
	v_cmp_le_f32_e64 s[16:17], |v136|, s76
	v_mul_f32_e64 v134, v193, |v134|
	v_mul_f32_e64 v136, v193, |v136|
	v_fmac_f32_e32 v134, 0x3e0293ee, v89
	v_fmac_f32_e32 v136, 0x3e0293ee, v73
	v_cndmask_b32_e32 v89, v234, v134, vcc
	v_cndmask_b32_e64 v73, v234, v136, s[16:17]
	v_add_f32_e32 v134, 0xc1000000, v135
	v_add_f32_e32 v136, 0xc2200000, v135
	v_cmp_le_f32_e64 vcc, |v134|, s76
	v_cmp_le_f32_e64 s[16:17], |v136|, s76
	v_mul_f32_e64 v134, v193, |v134|
	v_mul_f32_e64 v136, v193, |v136|
	v_fmac_f32_e32 v134, 0x3e0293ee, v90
	v_fmac_f32_e32 v136, 0x3e0293ee, v74
	v_cndmask_b32_e32 v90, v234, v134, vcc
	v_cndmask_b32_e64 v74, v234, v136, s[16:17]
	v_add_f32_e32 v134, 0xc1100000, v135
	v_add_f32_e32 v136, 0xc2240000, v135
	v_cmp_le_f32_e64 vcc, |v134|, s76
	v_cmp_le_f32_e64 s[16:17], |v136|, s76
	v_mul_f32_e64 v134, v193, |v134|
	v_mul_f32_e64 v136, v193, |v136|
	v_fmac_f32_e32 v134, 0x3e0293ee, v91
	v_fmac_f32_e32 v136, 0x3e0293ee, v75
	v_cndmask_b32_e32 v91, v234, v134, vcc
	v_cndmask_b32_e64 v75, v234, v136, s[16:17]
	v_add_f32_e32 v134, 0xc1200000, v135
	v_add_f32_e32 v136, 0xc2280000, v135
	v_cmp_le_f32_e64 vcc, |v134|, s76
	v_cmp_le_f32_e64 s[16:17], |v136|, s76
	v_mul_f32_e64 v134, v193, |v134|
	v_mul_f32_e64 v136, v193, |v136|
	v_fmac_f32_e32 v134, 0x3e0293ee, v92
	v_fmac_f32_e32 v136, 0x3e0293ee, v76
	v_cndmask_b32_e32 v92, v234, v134, vcc
	v_cndmask_b32_e64 v76, v234, v136, s[16:17]
	v_add_f32_e32 v134, 0xc1300000, v135
	v_add_f32_e32 v136, 0xc22c0000, v135
	v_cmp_le_f32_e64 vcc, |v134|, s76
	v_cmp_le_f32_e64 s[16:17], |v136|, s76
	v_mul_f32_e64 v134, v193, |v134|
	v_mul_f32_e64 v136, v193, |v136|
	v_fmac_f32_e32 v134, 0x3e0293ee, v93
	v_fmac_f32_e32 v136, 0x3e0293ee, v77
	v_cndmask_b32_e32 v93, v234, v134, vcc
	v_cndmask_b32_e64 v77, v234, v136, s[16:17]
	v_add_f32_e32 v134, 0xc1800000, v135
	v_add_f32_e32 v136, 0xc2400000, v135
	v_cmp_le_f32_e64 vcc, |v134|, s76
	v_cmp_le_f32_e64 s[16:17], |v136|, s76
	v_mul_f32_e64 v134, v193, |v134|
	v_mul_f32_e64 v136, v193, |v136|
	v_fmac_f32_e32 v134, 0x3e0293ee, v94
	v_fmac_f32_e32 v136, 0x3e0293ee, v78
	v_cndmask_b32_e32 v94, v234, v134, vcc
	v_cndmask_b32_e64 v78, v234, v136, s[16:17]
	v_add_f32_e32 v134, 0xc1880000, v135
	v_add_f32_e32 v136, 0xc2440000, v135
	v_cmp_le_f32_e64 vcc, |v134|, s76
	v_cmp_le_f32_e64 s[16:17], |v136|, s76
	v_mul_f32_e64 v134, v193, |v134|
	v_mul_f32_e64 v136, v193, |v136|
	v_fmac_f32_e32 v134, 0x3e0293ee, v95
	v_fmac_f32_e32 v136, 0x3e0293ee, v79
	v_cndmask_b32_e32 v95, v234, v134, vcc
	v_cndmask_b32_e64 v79, v234, v136, s[16:17]
	v_add_f32_e32 v134, 0xc1900000, v135
	v_add_f32_e32 v136, 0xc2480000, v135
	v_cmp_le_f32_e64 vcc, |v134|, s76
	v_cmp_le_f32_e64 s[16:17], |v136|, s76
	v_mul_f32_e64 v134, v193, |v134|
	v_mul_f32_e64 v136, v193, |v136|
	v_fmac_f32_e32 v134, 0x3e0293ee, v96
	v_fmac_f32_e32 v136, 0x3e0293ee, v80
	v_cndmask_b32_e32 v96, v234, v134, vcc
	v_cndmask_b32_e64 v80, v234, v136, s[16:17]
	v_add_f32_e32 v134, 0xc1980000, v135
	v_add_f32_e32 v136, 0xc24c0000, v135
	v_cmp_le_f32_e64 vcc, |v134|, s76
	v_cmp_le_f32_e64 s[16:17], |v136|, s76
	v_mul_f32_e64 v134, v193, |v134|
	v_mul_f32_e64 v136, v193, |v136|
	v_fmac_f32_e32 v134, 0x3e0293ee, v97
	v_fmac_f32_e32 v136, 0x3e0293ee, v81
	v_cndmask_b32_e32 v97, v234, v134, vcc
	v_cndmask_b32_e64 v81, v234, v136, s[16:17]
	v_add_f32_e32 v134, 0xc1c00000, v135
	v_add_f32_e32 v136, 0xc2600000, v135
	v_cmp_le_f32_e64 vcc, |v134|, s76
	v_cmp_le_f32_e64 s[16:17], |v136|, s76
	v_mul_f32_e64 v134, v193, |v134|
	v_mul_f32_e64 v136, v193, |v136|
	v_fmac_f32_e32 v134, 0x3e0293ee, v98
	v_fmac_f32_e32 v136, 0x3e0293ee, v82
	v_cndmask_b32_e32 v98, v234, v134, vcc
	v_cndmask_b32_e64 v82, v234, v136, s[16:17]
	v_add_f32_e32 v134, 0xc1c80000, v135
	v_add_f32_e32 v136, 0xc2640000, v135
	v_cmp_le_f32_e64 vcc, |v134|, s76
	v_cmp_le_f32_e64 s[16:17], |v136|, s76
	v_mul_f32_e64 v134, v193, |v134|
	v_mul_f32_e64 v136, v193, |v136|
	v_fmac_f32_e32 v134, 0x3e0293ee, v99
	v_fmac_f32_e32 v136, 0x3e0293ee, v83
	v_cndmask_b32_e32 v99, v234, v134, vcc
	v_cndmask_b32_e64 v83, v234, v136, s[16:17]
	v_add_f32_e32 v134, 0xc1d00000, v135
	v_add_f32_e32 v136, 0xc2680000, v135
	v_cmp_le_f32_e64 vcc, |v134|, s76
	v_cmp_le_f32_e64 s[16:17], |v136|, s76
	v_mul_f32_e64 v134, v193, |v134|
	v_mul_f32_e64 v136, v193, |v136|
	v_fmac_f32_e32 v134, 0x3e0293ee, v100
	v_fmac_f32_e32 v136, 0x3e0293ee, v84
	v_cndmask_b32_e32 v100, v234, v134, vcc
	v_cndmask_b32_e64 v84, v234, v136, s[16:17]
	v_add_f32_e32 v134, 0xc1d80000, v135
	v_add_f32_e32 v136, 0xc26c0000, v135
	v_cmp_le_f32_e64 vcc, |v134|, s76
	v_cmp_le_f32_e64 s[16:17], |v136|, s76
	v_mul_f32_e64 v134, v193, |v134|
	v_mul_f32_e64 v136, v193, |v136|
	v_fmac_f32_e32 v134, 0x3e0293ee, v101
	v_fmac_f32_e32 v136, 0x3e0293ee, v85
	v_cndmask_b32_e32 v101, v234, v134, vcc
	v_cndmask_b32_e64 v85, v234, v136, s[16:17]
	s_branch .Lam_done_4

.Lam_done_4:
	v_max_f32_e32 v134, v86, v87
	v_max3_f32 v134, v134, v88, v89
	v_max3_f32 v134, v134, v90, v91
	v_max3_f32 v134, v134, v92, v93
	v_max3_f32 v134, v134, v94, v95
	v_max3_f32 v134, v134, v96, v97
	v_max3_f32 v134, v134, v98, v99
	v_max3_f32 v134, v134, v100, v101
	v_max3_f32 v134, v134, v70, v71
	v_max3_f32 v134, v134, v72, v73
	v_max3_f32 v134, v134, v74, v75
	v_max3_f32 v134, v134, v76, v77
	v_max3_f32 v134, v134, v78, v79
	v_max3_f32 v134, v134, v80, v81
	v_max3_f32 v134, v134, v82, v83
	v_max3_f32 v134, v134, v84, v85
	v_mov_b32_e32 v135, v134
	s_nop 1
	v_permlane32_swap_b32_e32 v134, v135
	v_max3_f32 v210, v209, v134, v135
	v_sub_f32_e32 v86, v86, v210
	v_exp_f32_e32 v135, v86
	v_sub_f32_e32 v86, v87, v210
	v_exp_f32_e32 v136, v86
	v_sub_f32_e32 v86, v88, v210
	v_exp_f32_e32 v137, v86
	v_sub_f32_e32 v86, v89, v210
	v_exp_f32_e32 v89, v86
	v_sub_f32_e32 v86, v90, v210
	v_exp_f32_e32 v90, v86
	v_sub_f32_e32 v86, v91, v210
	v_exp_f32_e32 v91, v86
	v_sub_f32_e32 v86, v92, v210
	v_exp_f32_e32 v92, v86
	v_sub_f32_e32 v86, v93, v210
	v_exp_f32_e32 v93, v86
	v_sub_f32_e32 v86, v94, v210
	v_exp_f32_e32 v94, v86
	v_sub_f32_e32 v86, v95, v210
	v_exp_f32_e32 v95, v86
	v_sub_f32_e32 v86, v96, v210
	v_exp_f32_e32 v96, v86
	v_sub_f32_e32 v86, v97, v210
	v_exp_f32_e32 v97, v86
	v_sub_f32_e32 v86, v98, v210
	v_exp_f32_e32 v98, v86
	v_sub_f32_e32 v86, v99, v210
	v_exp_f32_e32 v99, v86
	v_sub_f32_e32 v86, v100, v210
	v_sub_f32_e32 v134, v209, v210
	v_sub_f32_e32 v74, v74, v210
	v_exp_f32_e32 v100, v86
	v_sub_f32_e32 v86, v101, v210
	v_exp_f32_e32 v101, v86
	v_exp_f32_e32 v86, v134
	v_exp_f32_e32 v134, v74
	v_add_f32_e32 v74, 0, v135
	v_add_f32_e32 v74, v136, v74
	v_add_f32_e32 v74, v137, v74
	v_add_f32_e32 v74, v89, v74
	v_add_f32_e32 v74, v90, v74
	v_add_f32_e32 v74, v91, v74
	v_add_f32_e32 v74, v92, v74
	v_add_f32_e32 v74, v93, v74
	v_add_f32_e32 v74, v94, v74
	v_add_f32_e32 v74, v95, v74
	v_add_f32_e32 v74, v96, v74
	v_sub_f32_e32 v70, v70, v210
	v_add_f32_e32 v74, v97, v74
	v_sub_f32_e32 v71, v71, v210
	v_exp_f32_e32 v70, v70
	v_add_f32_e32 v74, v98, v74
	v_sub_f32_e32 v72, v72, v210
	v_exp_f32_e32 v71, v71
	v_add_f32_e32 v74, v99, v74
	v_sub_f32_e32 v73, v73, v210
	v_exp_f32_e32 v72, v72
	v_add_f32_e32 v74, v100, v74
	v_exp_f32_e32 v73, v73
	v_add_f32_e32 v74, v101, v74
	v_sub_f32_e32 v75, v75, v210
	v_add_f32_e32 v74, v70, v74
	v_sub_f32_e32 v76, v76, v210
	v_exp_f32_e32 v138, v75
	v_add_f32_e32 v74, v71, v74
	v_sub_f32_e32 v77, v77, v210
	v_exp_f32_e32 v139, v76
	v_add_f32_e32 v74, v72, v74
	v_sub_f32_e32 v78, v78, v210
	v_exp_f32_e32 v77, v77
	v_add_f32_e32 v74, v73, v74
	v_sub_f32_e32 v79, v79, v210
	v_exp_f32_e32 v140, v78
	v_add_f32_e32 v74, v134, v74
	v_sub_f32_e32 v80, v80, v210
	v_exp_f32_e32 v141, v79
	v_add_f32_e32 v74, v138, v74
	v_sub_f32_e32 v81, v81, v210
	v_exp_f32_e32 v174, v80
	v_add_f32_e32 v74, v139, v74
	v_sub_f32_e32 v82, v82, v210
	v_exp_f32_e32 v175, v81
	v_add_f32_e32 v74, v77, v74
	v_sub_f32_e32 v83, v83, v210
	v_exp_f32_e32 v176, v82
	v_add_f32_e32 v74, v140, v74
	v_sub_f32_e32 v84, v84, v210
	v_exp_f32_e32 v177, v83
	v_add_f32_e32 v74, v141, v74
	v_sub_f32_e32 v85, v85, v210
	v_exp_f32_e32 v178, v84
	v_add_f32_e32 v74, v174, v74
	v_exp_f32_e32 v179, v85
	v_add_f32_e32 v74, v175, v74
	v_add_f32_e32 v74, v176, v74
	v_add_f32_e32 v74, v177, v74
	v_add_f32_e32 v74, v178, v74
	v_add_f32_e32 v87, v179, v74
	v_mov_b32_e32 v88, v87
	s_nop 1
	v_permlane32_swap_b32_e32 v87, v88
	v_cmp_gt_f32_e32 vcc, 1.0, v86
	v_cvt_pk_bf16_f32 v82, v135, v136
	v_cvt_pk_bf16_f32 v83, v137, v89
	v_cvt_pk_bf16_f32 v84, v90, v91
	v_cvt_pk_bf16_f32 v85, v92, v93
	v_cvt_pk_bf16_f32 v78, v94, v95
	v_cvt_pk_bf16_f32 v79, v96, v97
	v_cvt_pk_bf16_f32 v80, v98, v99
	v_cvt_pk_bf16_f32 v81, v100, v101
	v_cvt_pk_bf16_f32 v74, v70, v71
	v_cvt_pk_bf16_f32 v75, v72, v73
	v_cvt_pk_bf16_f32 v76, v134, v138
	v_cvt_pk_bf16_f32 v77, v139, v77
	v_cvt_pk_bf16_f32 v70, v140, v141
	v_cvt_pk_bf16_f32 v71, v174, v175
	v_cvt_pk_bf16_f32 v72, v176, v177
	v_cvt_pk_bf16_f32 v73, v178, v179
	s_cbranch_vccz .LBB0_587
	s_and_saveexec_b64 s[26:27], s[38:39]
	ds_write_b32 v191, v86 offset:128
	s_or_b64 exec, exec, s[26:27]
	s_waitcnt lgkmcnt(0)
	v_lshl_add_u32 v89, v185, 2, s44
	ds_read_b128 v[90:93], v89 offset:224
	ds_read_b128 v[94:97], v89 offset:192
	ds_read_b128 v[98:101], v89 offset:160
	ds_read_b128 v[134:137], v89 offset:128
	s_waitcnt lgkmcnt(3)
	v_pk_mul_f32 v[34:35], v[34:35], v[92:93]
	s_waitcnt lgkmcnt(2)
	v_pk_mul_f32 v[30:31], v[30:31], v[96:97]
	s_waitcnt lgkmcnt(1)
	v_pk_mul_f32 v[26:27], v[26:27], v[100:101]
	s_waitcnt lgkmcnt(0)
	v_pk_mul_f32 v[22:23], v[22:23], v[136:137]
	v_pk_mul_f32 v[32:33], v[32:33], v[90:91]
	v_pk_mul_f32 v[28:29], v[28:29], v[94:95]
	v_pk_mul_f32 v[24:25], v[24:25], v[98:99]
	v_pk_mul_f32 v[20:21], v[20:21], v[134:135]
	v_pk_mul_f32 v[50:51], v[50:51], v[92:93]
	v_pk_mul_f32 v[46:47], v[46:47], v[96:97]
	v_pk_mul_f32 v[42:43], v[42:43], v[100:101]
	v_pk_mul_f32 v[38:39], v[38:39], v[136:137]
	v_pk_mul_f32 v[48:49], v[48:49], v[90:91]
	v_pk_mul_f32 v[44:45], v[44:45], v[94:95]
	v_pk_mul_f32 v[40:41], v[40:41], v[98:99]
	v_pk_mul_f32 v[36:37], v[36:37], v[134:135]
	v_pk_mul_f32 v[66:67], v[66:67], v[92:93]
	v_pk_mul_f32 v[62:63], v[62:63], v[96:97]
	v_pk_mul_f32 v[58:59], v[58:59], v[100:101]
	v_pk_mul_f32 v[54:55], v[54:55], v[136:137]
	v_pk_mul_f32 v[64:65], v[64:65], v[90:91]
	v_pk_mul_f32 v[60:61], v[60:61], v[94:95]
	v_pk_mul_f32 v[56:57], v[56:57], v[98:99]
	v_pk_mul_f32 v[52:53], v[52:53], v[134:135]
	v_pk_mul_f32 v[18:19], v[18:19], v[92:93]
	v_pk_mul_f32 v[14:15], v[14:15], v[96:97]
	v_pk_mul_f32 v[10:11], v[10:11], v[100:101]
	v_pk_mul_f32 v[6:7], v[6:7], v[136:137]
	v_pk_mul_f32 v[16:17], v[16:17], v[90:91]
	v_pk_mul_f32 v[12:13], v[12:13], v[94:95]
	v_pk_mul_f32 v[8:9], v[8:9], v[98:99]
	v_pk_mul_f32 v[4:5], v[4:5], v[134:135]

.LBB0_589:
	v_add_u32_e32 v72, s47, v195
	v_add_u32_e32 v73, 32, v72
	v_min_i32_e32 v70, s51, v72
	v_cmp_lt_i32_e32 vcc, -1, v72
	s_movk_i32 s16, 0xffdf
	v_min_i32_e32 v73, s51, v73
	v_cndmask_b32_e32 v70, 0, v70, vcc
	v_cmp_lt_i32_e32 vcc, s16, v72
	v_ashrrev_i32_e32 v71, 31, v70
	v_lshlrev_b64 v[70:71], s50, v[70:71]
	v_cndmask_b32_e32 v72, 0, v73, vcc
	v_ashrrev_i32_e32 v73, 31, v72
	v_lshl_add_u64 v[70:71], v[2:3], 0, v[70:71]
	v_lshlrev_b64 v[72:73], s50, v[72:73]
	v_lshlrev_b64 v[70:71], 1, v[70:71]
	v_lshl_add_u64 v[72:73], v[2:3], 0, v[72:73]
	v_lshl_add_u64 v[74:75], s[18:19], 0, v[70:71]
	v_lshlrev_b64 v[72:73], 1, v[72:73]
	v_lshl_add_u64 v[76:77], s[18:19], 0, v[72:73]
	v_lshl_add_u64 v[70:71], s[12:13], 0, v[70:71]
	v_lshl_add_u64 v[72:73], s[12:13], 0, v[72:73]
	s_waitcnt vmcnt(4)
	s_waitcnt vmcnt(7)
	ds_write_b128 v196, v[142:145] offset:16384
	s_waitcnt vmcnt(6)
	ds_write_b128 v197, v[146:149] offset:16384
	s_waitcnt vmcnt(4)
	ds_write_b128 v198, v[170:173] offset:49152
	ds_write_b128 v199, v[166:169] offset:49152
	s_waitcnt lgkmcnt(0)
	s_barrier
	global_load_dwordx4 v[134:137], v[74:75], off
	global_load_dwordx4 v[138:141], v[76:77], off
	global_load_dwordx4 v[142:145], v[70:71], off
	global_load_dwordx4 v[146:149], v[72:73], off
	s_lshl_b64 s[22:23], s[22:23], 7
	s_add_i32 s46, s46, -3
	s_cmp_gt_u32 s46, 2
	s_cbranch_scc1 .LBB0_595
	ds_read_b128 v[70:73], v207 offset:49152
	ds_read_b128 v[74:77], v207 offset:57344
	ds_read_b128 v[166:169], v206 offset:49152
	ds_read_b128 v[170:173], v206 offset:57344
	s_waitcnt lgkmcnt(3)
	v_mfma_f32_32x32x16_bf16 v[86:101], v[70:73], v[110:113], 0
	s_waitcnt lgkmcnt(2)
	v_mfma_f32_32x32x16_bf16 v[70:85], v[74:77], v[110:113], 0
	ds_read_b128 v[110:113], v205 offset:49152
	ds_read_b128 v[196:199], v205 offset:57344
	s_waitcnt lgkmcnt(3)
	v_mfma_f32_32x32x16_bf16 v[86:101], v[166:169], v[130:133], v[86:101]
	s_waitcnt lgkmcnt(2)
	v_mfma_f32_32x32x16_bf16 v[70:85], v[170:173], v[130:133], v[70:85]
	ds_read_b128 v[130:133], v204 offset:49152
	ds_read_b128 v[166:169], v204 offset:57344
	s_waitcnt lgkmcnt(3)
	v_mfma_f32_32x32x16_bf16 v[86:101], v[110:113], v[126:129], v[86:101]
	s_waitcnt lgkmcnt(2)
	v_mfma_f32_32x32x16_bf16 v[70:85], v[196:199], v[126:129], v[70:85]
	ds_read_b128 v[110:113], v203 offset:49152
	ds_read_b128 v[126:129], v203 offset:57344
	s_waitcnt lgkmcnt(3)
	v_mfma_f32_32x32x16_bf16 v[86:101], v[130:133], v[122:125], v[86:101]
	s_waitcnt lgkmcnt(2)
	v_mfma_f32_32x32x16_bf16 v[70:85], v[166:169], v[122:125], v[70:85]
	ds_read_b128 v[122:125], v202 offset:49152
	ds_read_b128 v[130:133], v202 offset:57344
	s_waitcnt lgkmcnt(3)
	v_mfma_f32_32x32x16_bf16 v[86:101], v[110:113], v[118:121], v[86:101]
	s_waitcnt lgkmcnt(2)
	v_mfma_f32_32x32x16_bf16 v[70:85], v[126:129], v[118:121], v[70:85]
	ds_read_b128 v[110:113], v201 offset:49152
	ds_read_b128 v[118:121], v201 offset:57344
	s_waitcnt lgkmcnt(3)
	v_mfma_f32_32x32x16_bf16 v[86:101], v[122:125], v[114:117], v[86:101]
	s_waitcnt lgkmcnt(2)
	v_mfma_f32_32x32x16_bf16 v[70:85], v[130:133], v[114:117], v[70:85]
	ds_read_b128 v[114:117], v200 offset:49152
	ds_read_b128 v[122:125], v200 offset:57344
	s_waitcnt lgkmcnt(3)
	v_mfma_f32_32x32x16_bf16 v[86:101], v[110:113], v[106:109], v[86:101]
	s_waitcnt lgkmcnt(2)
	v_mfma_f32_32x32x16_bf16 v[70:85], v[118:121], v[106:109], v[70:85]
	s_waitcnt lgkmcnt(1)
	v_mfma_f32_32x32x16_bf16 v[86:101], v[114:117], v[102:105], v[86:101]
	s_waitcnt lgkmcnt(0)
	v_mfma_f32_32x32x16_bf16 v[70:85], v[122:125], v[102:105], v[70:85]
	v_add_u32_e32 v102, 0x140, v194
	v_sub_u32_e32 v103, v192, v102
	v_cvt_f32_i32_e32 v103, v103
	v_readfirstlane_b32 s40, v102
	s_add_i32 s41, s40, 64
	s_cmp_lt_i32 s40, 0
	s_cbranch_scc1 .Lam_out_5
	s_cmp_gt_i32 s41, s45
	s_cbranch_scc1 .Lam_out_5
	v_add_f32_e32 v104, 0xc2000000, v103
	v_mov_b32_e32 v105, v103
	v_cmp_le_f32_e64 vcc, |v104|, s76
	v_cmp_le_f32_e64 s[12:13], |v105|, s76
	v_mul_f32_e64 v104, v193, |v104|
	v_mul_f32_e64 v105, v193, |v105|
	v_fmac_f32_e32 v104, 0x3e0293ee, v70
	v_fmac_f32_e32 v105, 0x3e0293ee, v86
	v_cndmask_b32_e32 v70, v234, v104, vcc
	v_cndmask_b32_e64 v102, v234, v105, s[12:13]
	v_add_f32_e32 v104, -1.0, v103
	v_add_f32_e32 v105, 0xc2040000, v103
	v_cmp_le_f32_e64 vcc, |v104|, s76
	v_cmp_le_f32_e64 s[12:13], |v105|, s76
	v_mul_f32_e64 v104, v193, |v104|
	v_mul_f32_e64 v105, v193, |v105|
	v_fmac_f32_e32 v104, 0x3e0293ee, v87
	v_fmac_f32_e32 v105, 0x3e0293ee, v71
	v_cndmask_b32_e32 v87, v234, v104, vcc
	v_cndmask_b32_e64 v71, v234, v105, s[12:13]
	v_add_f32_e32 v104, -2.0, v103
	v_add_f32_e32 v105, 0xc2080000, v103
	v_cmp_le_f32_e64 vcc, |v104|, s76
	v_cmp_le_f32_e64 s[12:13], |v105|, s76
	v_mul_f32_e64 v104, v193, |v104|
	v_mul_f32_e64 v105, v193, |v105|
	v_fmac_f32_e32 v104, 0x3e0293ee, v88
	v_fmac_f32_e32 v105, 0x3e0293ee, v72
	v_cndmask_b32_e32 v88, v234, v104, vcc
	v_cndmask_b32_e64 v72, v234, v105, s[12:13]
	v_add_f32_e32 v104, 0xc0400000, v103
	v_add_f32_e32 v105, 0xc20c0000, v103
	v_cmp_le_f32_e64 vcc, |v104|, s76
	v_cmp_le_f32_e64 s[12:13], |v105|, s76
	v_mul_f32_e64 v104, v193, |v104|
	v_mul_f32_e64 v105, v193, |v105|
	v_fmac_f32_e32 v104, 0x3e0293ee, v89
	v_fmac_f32_e32 v105, 0x3e0293ee, v73
	v_cndmask_b32_e32 v89, v234, v104, vcc
	v_cndmask_b32_e64 v73, v234, v105, s[12:13]
	v_add_f32_e32 v104, 0xc1000000, v103
	v_add_f32_e32 v105, 0xc2200000, v103
	v_cmp_le_f32_e64 vcc, |v104|, s76
	v_cmp_le_f32_e64 s[12:13], |v105|, s76
	v_mul_f32_e64 v104, v193, |v104|
	v_mul_f32_e64 v105, v193, |v105|
	v_fmac_f32_e32 v104, 0x3e0293ee, v90
	v_fmac_f32_e32 v105, 0x3e0293ee, v74
	v_cndmask_b32_e32 v90, v234, v104, vcc
	v_cndmask_b32_e64 v74, v234, v105, s[12:13]
	v_add_f32_e32 v104, 0xc1100000, v103
	v_add_f32_e32 v105, 0xc2240000, v103
	v_cmp_le_f32_e64 vcc, |v104|, s76
	v_cmp_le_f32_e64 s[12:13], |v105|, s76
	v_mul_f32_e64 v104, v193, |v104|
	v_mul_f32_e64 v105, v193, |v105|
	v_fmac_f32_e32 v104, 0x3e0293ee, v91
	v_fmac_f32_e32 v105, 0x3e0293ee, v75
	v_cndmask_b32_e32 v91, v234, v104, vcc
	v_cndmask_b32_e64 v75, v234, v105, s[12:13]
	v_add_f32_e32 v104, 0xc1200000, v103
	v_add_f32_e32 v105, 0xc2280000, v103
	v_cmp_le_f32_e64 vcc, |v104|, s76
	v_cmp_le_f32_e64 s[12:13], |v105|, s76
	v_mul_f32_e64 v104, v193, |v104|
	v_mul_f32_e64 v105, v193, |v105|
	v_fmac_f32_e32 v104, 0x3e0293ee, v92
	v_fmac_f32_e32 v105, 0x3e0293ee, v76
	v_cndmask_b32_e32 v92, v234, v104, vcc
	v_cndmask_b32_e64 v76, v234, v105, s[12:13]
	v_add_f32_e32 v104, 0xc1300000, v103
	v_add_f32_e32 v105, 0xc22c0000, v103
	v_cmp_le_f32_e64 vcc, |v104|, s76
	v_cmp_le_f32_e64 s[12:13], |v105|, s76
	v_mul_f32_e64 v104, v193, |v104|
	v_mul_f32_e64 v105, v193, |v105|
	v_fmac_f32_e32 v104, 0x3e0293ee, v93
	v_fmac_f32_e32 v105, 0x3e0293ee, v77
	v_cndmask_b32_e32 v93, v234, v104, vcc
	v_cndmask_b32_e64 v77, v234, v105, s[12:13]
	v_add_f32_e32 v104, 0xc1800000, v103
	v_add_f32_e32 v105, 0xc2400000, v103
	v_cmp_le_f32_e64 vcc, |v104|, s76
	v_cmp_le_f32_e64 s[12:13], |v105|, s76
	v_mul_f32_e64 v104, v193, |v104|
	v_mul_f32_e64 v105, v193, |v105|
	v_fmac_f32_e32 v104, 0x3e0293ee, v94
	v_fmac_f32_e32 v105, 0x3e0293ee, v78
	v_cndmask_b32_e32 v94, v234, v104, vcc
	v_cndmask_b32_e64 v78, v234, v105, s[12:13]
	v_add_f32_e32 v104, 0xc1880000, v103
	v_add_f32_e32 v105, 0xc2440000, v103
	v_cmp_le_f32_e64 vcc, |v104|, s76
	v_cmp_le_f32_e64 s[12:13], |v105|, s76
	v_mul_f32_e64 v104, v193, |v104|
	v_mul_f32_e64 v105, v193, |v105|
	v_fmac_f32_e32 v104, 0x3e0293ee, v95
	v_fmac_f32_e32 v105, 0x3e0293ee, v79
	v_cndmask_b32_e32 v95, v234, v104, vcc
	v_cndmask_b32_e64 v79, v234, v105, s[12:13]
	v_add_f32_e32 v104, 0xc1900000, v103
	v_add_f32_e32 v105, 0xc2480000, v103
	v_cmp_le_f32_e64 vcc, |v104|, s76
	v_cmp_le_f32_e64 s[12:13], |v105|, s76
	v_mul_f32_e64 v104, v193, |v104|
	v_mul_f32_e64 v105, v193, |v105|
	v_fmac_f32_e32 v104, 0x3e0293ee, v96
	v_fmac_f32_e32 v105, 0x3e0293ee, v80
	v_cndmask_b32_e32 v96, v234, v104, vcc
	v_cndmask_b32_e64 v80, v234, v105, s[12:13]
	v_add_f32_e32 v104, 0xc1980000, v103
	v_add_f32_e32 v105, 0xc24c0000, v103
	v_cmp_le_f32_e64 vcc, |v104|, s76
	v_cmp_le_f32_e64 s[12:13], |v105|, s76
	v_mul_f32_e64 v104, v193, |v104|
	v_mul_f32_e64 v105, v193, |v105|
	v_fmac_f32_e32 v104, 0x3e0293ee, v97
	v_fmac_f32_e32 v105, 0x3e0293ee, v81
	v_cndmask_b32_e32 v97, v234, v104, vcc
	v_cndmask_b32_e64 v81, v234, v105, s[12:13]
	v_add_f32_e32 v104, 0xc1c00000, v103
	v_add_f32_e32 v105, 0xc2600000, v103
	v_cmp_le_f32_e64 vcc, |v104|, s76
	v_cmp_le_f32_e64 s[12:13], |v105|, s76
	v_mul_f32_e64 v104, v193, |v104|
	v_mul_f32_e64 v105, v193, |v105|
	v_fmac_f32_e32 v104, 0x3e0293ee, v98
	v_fmac_f32_e32 v105, 0x3e0293ee, v82
	v_cndmask_b32_e32 v98, v234, v104, vcc
	v_cndmask_b32_e64 v82, v234, v105, s[12:13]
	v_add_f32_e32 v104, 0xc1c80000, v103
	v_add_f32_e32 v105, 0xc2640000, v103
	v_cmp_le_f32_e64 vcc, |v104|, s76
	v_cmp_le_f32_e64 s[12:13], |v105|, s76
	v_mul_f32_e64 v104, v193, |v104|
	v_mul_f32_e64 v105, v193, |v105|
	v_fmac_f32_e32 v104, 0x3e0293ee, v99
	v_fmac_f32_e32 v105, 0x3e0293ee, v83
	v_cndmask_b32_e32 v99, v234, v104, vcc
	v_cndmask_b32_e64 v83, v234, v105, s[12:13]
	v_add_f32_e32 v104, 0xc1d00000, v103
	v_add_f32_e32 v105, 0xc2680000, v103
	v_cmp_le_f32_e64 vcc, |v104|, s76
	v_cmp_le_f32_e64 s[12:13], |v105|, s76
	v_mul_f32_e64 v104, v193, |v104|
	v_mul_f32_e64 v105, v193, |v105|
	v_fmac_f32_e32 v104, 0x3e0293ee, v100
	v_fmac_f32_e32 v105, 0x3e0293ee, v84
	v_cndmask_b32_e32 v100, v234, v104, vcc
	v_cndmask_b32_e64 v84, v234, v105, s[12:13]
	v_add_f32_e32 v104, 0xc1d80000, v103
	v_add_f32_e32 v105, 0xc26c0000, v103
	v_cmp_le_f32_e64 vcc, |v104|, s76
	v_cmp_le_f32_e64 s[12:13], |v105|, s76
	v_mul_f32_e64 v104, v193, |v104|
	v_mul_f32_e64 v105, v193, |v105|
	v_fmac_f32_e32 v104, 0x3e0293ee, v101
	v_fmac_f32_e32 v105, 0x3e0293ee, v85
	v_cndmask_b32_e32 v101, v234, v104, vcc
	v_cndmask_b32_e64 v85, v234, v105, s[12:13]
	s_branch .Lam_done_5
.Lam_out_5:
	s_nop 7
	v_mov_b32_e32 v70, v234
	v_mov_b32_e32 v102, v234
	v_mov_b32_e32 v87, v234
	v_mov_b32_e32 v71, v234
	v_mov_b32_e32 v88, v234
	v_mov_b32_e32 v72, v234
	v_mov_b32_e32 v89, v234
	v_mov_b32_e32 v73, v234
	v_mov_b32_e32 v90, v234
	v_mov_b32_e32 v74, v234
	v_mov_b32_e32 v91, v234
	v_mov_b32_e32 v75, v234
	v_mov_b32_e32 v92, v234
	v_mov_b32_e32 v76, v234
	v_mov_b32_e32 v93, v234
	v_mov_b32_e32 v77, v234
	v_mov_b32_e32 v94, v234
	v_mov_b32_e32 v78, v234
	v_mov_b32_e32 v95, v234
	v_mov_b32_e32 v79, v234
	v_mov_b32_e32 v96, v234
	v_mov_b32_e32 v80, v234
	v_mov_b32_e32 v97, v234
	v_mov_b32_e32 v81, v234
	v_mov_b32_e32 v98, v234
	v_mov_b32_e32 v82, v234
	v_mov_b32_e32 v99, v234
	v_mov_b32_e32 v83, v234
	v_mov_b32_e32 v100, v234
	v_mov_b32_e32 v84, v234
	v_mov_b32_e32 v101, v234
	v_mov_b32_e32 v85, v234
.Lam_done_5:
	v_max_f32_e32 v86, v102, v87
	v_max3_f32 v86, v86, v88, v89
	v_max3_f32 v86, v86, v90, v91
	v_max3_f32 v86, v86, v92, v93
	v_max3_f32 v86, v86, v94, v95
	v_max3_f32 v86, v86, v96, v97
	v_max3_f32 v86, v86, v98, v99
	v_max3_f32 v86, v86, v100, v101
	v_max3_f32 v86, v86, v70, v71
	v_max3_f32 v86, v86, v72, v73
	v_max3_f32 v86, v86, v74, v75
	v_max3_f32 v86, v86, v76, v77
	v_max3_f32 v86, v86, v78, v79
	v_max3_f32 v86, v86, v80, v81
	v_max3_f32 v86, v86, v82, v83
	v_max3_f32 v86, v86, v84, v85
	v_mov_b32_e32 v103, v86
	s_nop 1
	v_permlane32_swap_b32_e32 v86, v103
	v_max3_f32 v86, v210, v86, v103
	v_sub_f32_e32 v87, v87, v86
	v_exp_f32_e32 v104, v87
	v_sub_f32_e32 v87, v88, v86
	v_exp_f32_e32 v105, v87
	v_sub_f32_e32 v87, v89, v86
	v_exp_f32_e32 v106, v87
	v_sub_f32_e32 v87, v90, v86
	v_exp_f32_e32 v90, v87
	v_sub_f32_e32 v87, v91, v86
	v_exp_f32_e32 v91, v87
	v_sub_f32_e32 v87, v92, v86
	v_exp_f32_e32 v92, v87
	v_sub_f32_e32 v87, v93, v86
	v_exp_f32_e32 v93, v87
	v_sub_f32_e32 v87, v94, v86
	v_exp_f32_e32 v94, v87
	v_sub_f32_e32 v87, v95, v86
	v_exp_f32_e32 v95, v87
	v_sub_f32_e32 v87, v96, v86
	v_sub_f32_e32 v102, v102, v86
	v_exp_f32_e32 v96, v87
	v_sub_f32_e32 v87, v97, v86
	v_exp_f32_e32 v102, v102
	v_exp_f32_e32 v97, v87
	v_sub_f32_e32 v87, v98, v86
	v_exp_f32_e32 v98, v87
	v_sub_f32_e32 v87, v99, v86
	v_exp_f32_e32 v99, v87
	v_sub_f32_e32 v87, v100, v86
	v_sub_f32_e32 v103, v210, v86
	v_sub_f32_e32 v74, v74, v86
	v_exp_f32_e32 v100, v87
	v_sub_f32_e32 v87, v101, v86
	v_exp_f32_e32 v101, v87
	v_exp_f32_e32 v87, v103
	v_exp_f32_e32 v103, v74
	v_add_f32_e32 v74, 0, v102
	v_add_f32_e32 v74, v104, v74
	v_add_f32_e32 v74, v105, v74
	v_add_f32_e32 v74, v106, v74
	v_add_f32_e32 v74, v90, v74
	v_add_f32_e32 v74, v91, v74
	v_add_f32_e32 v74, v92, v74
	v_add_f32_e32 v74, v93, v74
	v_add_f32_e32 v74, v94, v74
	v_add_f32_e32 v74, v95, v74
	v_add_f32_e32 v74, v96, v74
	v_sub_f32_e32 v70, v70, v86
	v_add_f32_e32 v74, v97, v74
	v_sub_f32_e32 v71, v71, v86
	v_exp_f32_e32 v70, v70
	v_add_f32_e32 v74, v98, v74
	v_sub_f32_e32 v72, v72, v86
	v_exp_f32_e32 v71, v71
	v_add_f32_e32 v74, v99, v74
	v_sub_f32_e32 v73, v73, v86
	v_exp_f32_e32 v72, v72
	v_add_f32_e32 v74, v100, v74
	v_exp_f32_e32 v73, v73
	v_add_f32_e32 v74, v101, v74
	v_sub_f32_e32 v75, v75, v86
	v_add_f32_e32 v74, v70, v74
	v_sub_f32_e32 v76, v76, v86
	v_exp_f32_e32 v107, v75
	v_add_f32_e32 v74, v71, v74
	v_sub_f32_e32 v77, v77, v86
	v_exp_f32_e32 v108, v76
	v_add_f32_e32 v74, v72, v74
	v_sub_f32_e32 v78, v78, v86
	v_exp_f32_e32 v77, v77
	v_add_f32_e32 v74, v73, v74
	v_sub_f32_e32 v79, v79, v86
	v_exp_f32_e32 v109, v78
	v_add_f32_e32 v74, v103, v74
	v_sub_f32_e32 v80, v80, v86
	v_exp_f32_e32 v110, v79
	v_add_f32_e32 v74, v107, v74
	v_sub_f32_e32 v81, v81, v86
	v_exp_f32_e32 v111, v80
	v_add_f32_e32 v74, v108, v74
	v_sub_f32_e32 v82, v82, v86
	v_exp_f32_e32 v112, v81
	v_add_f32_e32 v74, v77, v74
	v_sub_f32_e32 v83, v83, v86
	v_exp_f32_e32 v113, v82
	v_add_f32_e32 v74, v109, v74
	v_sub_f32_e32 v84, v84, v86
	v_exp_f32_e32 v114, v83
	v_add_f32_e32 v74, v110, v74
	v_sub_f32_e32 v85, v85, v86
	v_exp_f32_e32 v115, v84
	v_add_f32_e32 v74, v111, v74
	v_exp_f32_e32 v116, v85
	v_add_f32_e32 v74, v112, v74
	v_add_f32_e32 v74, v113, v74
	v_add_f32_e32 v74, v114, v74
	v_add_f32_e32 v74, v115, v74
	v_add_f32_e32 v88, v116, v74
	v_mov_b32_e32 v89, v88
	s_nop 1
	v_permlane32_swap_b32_e32 v88, v89
	v_cmp_gt_f32_e32 vcc, 1.0, v87
	v_cvt_pk_bf16_f32 v82, v102, v104
	v_cvt_pk_bf16_f32 v83, v105, v106
	v_cvt_pk_bf16_f32 v84, v90, v91
	v_cvt_pk_bf16_f32 v85, v92, v93
	v_cvt_pk_bf16_f32 v78, v94, v95
	v_cvt_pk_bf16_f32 v79, v96, v97
	v_cvt_pk_bf16_f32 v80, v98, v99
	v_cvt_pk_bf16_f32 v81, v100, v101
	v_cvt_pk_bf16_f32 v74, v70, v71
	v_cvt_pk_bf16_f32 v75, v72, v73
	v_cvt_pk_bf16_f32 v76, v103, v107
	v_cvt_pk_bf16_f32 v77, v108, v77
	v_cvt_pk_bf16_f32 v70, v109, v110
	v_cvt_pk_bf16_f32 v71, v111, v112
	v_cvt_pk_bf16_f32 v72, v113, v114
	v_cvt_pk_bf16_f32 v73, v115, v116
	s_cbranch_vccz .LBB0_594
	s_and_saveexec_b64 s[12:13], s[38:39]
	ds_write_b32 v191, v87 offset:128
	s_or_b64 exec, exec, s[12:13]
	s_waitcnt lgkmcnt(0)
	v_lshl_add_u32 v102, v185, 2, s44
	ds_read_b128 v[90:93], v102 offset:224
	ds_read_b128 v[94:97], v102 offset:192
	ds_read_b128 v[98:101], v102 offset:160
	ds_read_b128 v[102:105], v102 offset:128
	s_waitcnt lgkmcnt(3)
	v_pk_mul_f32 v[34:35], v[34:35], v[92:93]
	s_waitcnt lgkmcnt(2)
	v_pk_mul_f32 v[30:31], v[30:31], v[96:97]
	s_waitcnt lgkmcnt(1)
	v_pk_mul_f32 v[26:27], v[26:27], v[100:101]
	s_waitcnt lgkmcnt(0)
	v_pk_mul_f32 v[22:23], v[22:23], v[104:105]
	v_pk_mul_f32 v[32:33], v[32:33], v[90:91]
	v_pk_mul_f32 v[28:29], v[28:29], v[94:95]
	v_pk_mul_f32 v[24:25], v[24:25], v[98:99]
	v_pk_mul_f32 v[20:21], v[20:21], v[102:103]
	v_pk_mul_f32 v[50:51], v[50:51], v[92:93]
	v_pk_mul_f32 v[46:47], v[46:47], v[96:97]
	v_pk_mul_f32 v[42:43], v[42:43], v[100:101]
	v_pk_mul_f32 v[38:39], v[38:39], v[104:105]
	v_pk_mul_f32 v[48:49], v[48:49], v[90:91]
	v_pk_mul_f32 v[44:45], v[44:45], v[94:95]
	v_pk_mul_f32 v[40:41], v[40:41], v[98:99]
	v_pk_mul_f32 v[36:37], v[36:37], v[102:103]
	v_pk_mul_f32 v[66:67], v[66:67], v[92:93]
	v_pk_mul_f32 v[62:63], v[62:63], v[96:97]
	v_pk_mul_f32 v[58:59], v[58:59], v[100:101]
	v_pk_mul_f32 v[54:55], v[54:55], v[104:105]
	v_pk_mul_f32 v[64:65], v[64:65], v[90:91]
	v_pk_mul_f32 v[60:61], v[60:61], v[94:95]
	v_pk_mul_f32 v[56:57], v[56:57], v[98:99]
	v_pk_mul_f32 v[52:53], v[52:53], v[102:103]
	v_pk_mul_f32 v[18:19], v[18:19], v[92:93]
	v_pk_mul_f32 v[14:15], v[14:15], v[96:97]
	v_pk_mul_f32 v[10:11], v[10:11], v[100:101]
	v_pk_mul_f32 v[6:7], v[6:7], v[104:105]
	v_pk_mul_f32 v[16:17], v[16:17], v[90:91]
	v_pk_mul_f32 v[12:13], v[12:13], v[94:95]
	v_pk_mul_f32 v[8:9], v[8:9], v[98:99]
	v_pk_mul_f32 v[4:5], v[4:5], v[102:103]
